# v37 + GEMM K-loops: load segment (LDS fragment reads + LDS-DMA issue) at s_setprio 2, MFMA block at 1 (timing-only)
# speedup vs baseline: 1.0019x; 1.0019x over previous
.LBB0_341:
	v_add_u32_e32 v2, s41, v173
	s_waitcnt lgkmcnt(0)
	ds_read_b128 v[142:145], v2
	ds_read_b128 v[146:149], v2 offset:1024
	ds_read_b128 v[150:153], v2 offset:2048
	ds_read_b128 v[154:157], v2 offset:3072
	v_add_u32_e32 v2, s82, v173
	ds_read_b128 v[158:161], v2
	ds_read_b128 v[162:165], v2 offset:1024
	ds_read_b128 v[166:169], v2 offset:2048
	ds_read_b128 v[180:183], v2 offset:3072
	s_add_i32 s21, s14, 2
	s_add_u32 s16, s12, 0x80
	s_addc_u32 s15, s13, 0
	s_cmp_eq_u32 s18, s14
	s_cselect_b32 s14, s60, s16
	s_cselect_b32 s66, s58, s4
	s_cselect_b32 s15, s61, s15
	s_cselect_b32 s22, s63, s7
	s_cselect_b32 s23, s62, s6
	s_cselect_b32 s17, s65, s20
	s_cselect_b32 s16, s64, s19
	v_lshl_add_u64 v[218:219], s[12:13], 0, v[140:141]
	s_add_i32 m0, s55, 0xc000
	ds_read_b128 v[184:187], v176
	ds_read_b128 v[188:191], v176 offset:1024
	ds_read_b128 v[192:195], v176 offset:2048
	ds_read_b128 v[196:199], v176 offset:3072
	ds_read_b128 v[200:203], v176 offset:4096
	ds_read_b128 v[204:207], v176 offset:5120
	ds_read_b128 v[210:213], v176 offset:6144
	ds_read_b128 v[214:217], v176 offset:7168
	global_load_lds_dwordx4 v[218:219], off
	v_lshl_add_u64 v[218:219], s[12:13], 0, v[4:5]
	s_add_i32 m0, s55, 0xe000
	s_nop 0
	global_load_lds_dwordx4 v[218:219], off
	s_waitcnt vmcnt(8)
	s_waitcnt lgkmcnt(0)
	s_barrier
	s_setprio 1
	s_waitcnt lgkmcnt(0)
	v_mfma_f32_16x16x32_bf16 v[130:133], v[142:145], v[184:187], v[130:133]
	v_mfma_f32_16x16x32_bf16 v[126:129], v[150:153], v[184:187], v[126:129]
	v_mfma_f32_16x16x32_bf16 v[122:125], v[142:145], v[192:195], v[122:125]
	v_mfma_f32_16x16x32_bf16 v[118:121], v[150:153], v[192:195], v[118:121]
	v_mfma_f32_16x16x32_bf16 v[114:117], v[142:145], v[200:203], v[114:117]
	v_mfma_f32_16x16x32_bf16 v[110:113], v[150:153], v[200:203], v[110:113]
	v_mfma_f32_16x16x32_bf16 v[106:109], v[142:145], v[210:213], v[106:109]
	v_mfma_f32_16x16x32_bf16 v[102:105], v[150:153], v[210:213], v[102:105]
	v_mfma_f32_16x16x32_bf16 v[130:133], v[146:149], v[188:191], v[130:133]
	v_mfma_f32_16x16x32_bf16 v[126:129], v[154:157], v[188:191], v[126:129]
	v_mfma_f32_16x16x32_bf16 v[122:125], v[146:149], v[196:199], v[122:125]
	v_mfma_f32_16x16x32_bf16 v[118:121], v[154:157], v[196:199], v[118:121]
	v_mfma_f32_16x16x32_bf16 v[114:117], v[146:149], v[204:207], v[114:117]
	v_mfma_f32_16x16x32_bf16 v[110:113], v[154:157], v[204:207], v[110:113]
	v_mfma_f32_16x16x32_bf16 v[106:109], v[146:149], v[214:217], v[106:109]
	v_mfma_f32_16x16x32_bf16 v[102:105], v[154:157], v[214:217], v[102:105]
	s_setprio 0
	s_setprio 1
	v_mfma_f32_16x16x32_bf16 v[98:101], v[158:161], v[184:187], v[98:101]
	v_mfma_f32_16x16x32_bf16 v[94:97], v[166:169], v[184:187], v[94:97]
	v_mfma_f32_16x16x32_bf16 v[90:93], v[158:161], v[192:195], v[90:93]
	v_mfma_f32_16x16x32_bf16 v[86:89], v[166:169], v[192:195], v[86:89]
	v_mfma_f32_16x16x32_bf16 v[82:85], v[158:161], v[200:203], v[82:85]
	v_mfma_f32_16x16x32_bf16 v[78:81], v[166:169], v[200:203], v[78:81]
	v_mfma_f32_16x16x32_bf16 v[74:77], v[158:161], v[210:213], v[74:77]
	v_mfma_f32_16x16x32_bf16 v[70:73], v[166:169], v[210:213], v[70:73]
	v_mfma_f32_16x16x32_bf16 v[98:101], v[162:165], v[188:191], v[98:101]
	v_mfma_f32_16x16x32_bf16 v[94:97], v[180:183], v[188:191], v[94:97]
	v_mfma_f32_16x16x32_bf16 v[90:93], v[162:165], v[196:199], v[90:93]
	v_mfma_f32_16x16x32_bf16 v[86:89], v[180:183], v[196:199], v[86:89]
	v_mfma_f32_16x16x32_bf16 v[82:85], v[162:165], v[204:207], v[82:85]
	v_mfma_f32_16x16x32_bf16 v[78:81], v[180:183], v[204:207], v[78:81]
	v_mfma_f32_16x16x32_bf16 v[74:77], v[162:165], v[214:217], v[74:77]
	v_mfma_f32_16x16x32_bf16 v[70:73], v[180:183], v[214:217], v[70:73]
	s_setprio 2
	s_barrier
	s_add_i32 s70, s41, s5
	v_mad_u64_u32 v[218:219], s[50:51], s66, v137, v[136:137]
	s_mov_b32 m0, s70
	v_mad_u64_u32 v[222:223], s[50:51], s66, v170, v[136:137]
	ds_read_b128 v[184:187], v176 offset:16384
	ds_read_b128 v[188:191], v176 offset:17408
	ds_read_b128 v[192:195], v176 offset:18432
	ds_read_b128 v[196:199], v176 offset:19456
	ds_read_b128 v[200:203], v176 offset:20480
	ds_read_b128 v[204:207], v176 offset:21504
	ds_read_b128 v[210:213], v176 offset:22528
	ds_read_b128 v[214:217], v176 offset:23552
	v_mov_b32_e32 v219, v3
	global_load_lds_dwordx4 v218, s[16:17]
	v_mov_b32_e32 v223, v3
	s_add_i32 m0, s70, 0x2000
	v_lshl_add_u64 v[220:221], s[16:17], 0, v[218:219]
	v_lshl_add_u64 v[224:225], s[16:17], 0, v[222:223]
	global_load_lds_dwordx4 v222, s[16:17]
	s_add_u32 s16, s16, s23
	s_addc_u32 s17, s17, s22
	s_add_i32 s50, s82, s5
	s_mov_b32 m0, s50
	v_lshl_add_u64 v[226:227], s[16:17], 0, v[218:219]
	global_load_lds_dwordx4 v218, s[16:17]
	s_add_i32 m0, s50, 0x2000
	v_lshl_add_u64 v[218:219], s[16:17], 0, v[222:223]
	global_load_lds_dwordx4 v222, s[16:17]
	v_mad_u64_u32 v[222:223], s[16:17], s66, v135, v[136:137]
	s_mov_b32 m0, s55
	v_mad_u64_u32 v[230:231], s[16:17], s66, v139, v[136:137]
	global_load_lds_dwordx4 v222, s[14:15]
	s_mov_b32 m0, s56
	v_mov_b32_e32 v223, v3
	global_load_lds_dwordx4 v230, s[14:15]
	s_waitcnt vmcnt(8)
	s_waitcnt lgkmcnt(0)
	v_mov_b32_e32 v231, v3
	v_lshl_add_u64 v[228:229], s[14:15], 0, v[222:223]
	v_lshl_add_u64 v[232:233], s[14:15], 0, v[230:231]
	s_barrier
	s_setprio 1
	s_waitcnt lgkmcnt(0)
	v_mfma_f32_16x16x32_bf16 v[66:69], v[142:145], v[184:187], v[66:69]
	v_mfma_f32_16x16x32_bf16 v[62:65], v[150:153], v[184:187], v[62:65]
	v_mfma_f32_16x16x32_bf16 v[58:61], v[142:145], v[192:195], v[58:61]
	v_mfma_f32_16x16x32_bf16 v[54:57], v[150:153], v[192:195], v[54:57]
	v_mfma_f32_16x16x32_bf16 v[50:53], v[142:145], v[200:203], v[50:53]
	v_mfma_f32_16x16x32_bf16 v[46:49], v[150:153], v[200:203], v[46:49]
	v_mfma_f32_16x16x32_bf16 v[42:45], v[142:145], v[210:213], v[42:45]
	v_mfma_f32_16x16x32_bf16 v[38:41], v[150:153], v[210:213], v[38:41]
	v_mfma_f32_16x16x32_bf16 v[66:69], v[146:149], v[188:191], v[66:69]
	v_mfma_f32_16x16x32_bf16 v[62:65], v[154:157], v[188:191], v[62:65]
	v_mfma_f32_16x16x32_bf16 v[58:61], v[146:149], v[196:199], v[58:61]
	v_mfma_f32_16x16x32_bf16 v[54:57], v[154:157], v[196:199], v[54:57]
	v_mfma_f32_16x16x32_bf16 v[50:53], v[146:149], v[204:207], v[50:53]
	v_mfma_f32_16x16x32_bf16 v[46:49], v[154:157], v[204:207], v[46:49]
	v_mfma_f32_16x16x32_bf16 v[42:45], v[146:149], v[214:217], v[42:45]
	v_mfma_f32_16x16x32_bf16 v[38:41], v[154:157], v[214:217], v[38:41]
	s_setprio 0
	s_setprio 1
	v_mfma_f32_16x16x32_bf16 v[34:37], v[158:161], v[184:187], v[34:37]
	v_mfma_f32_16x16x32_bf16 v[30:33], v[166:169], v[184:187], v[30:33]
	v_mfma_f32_16x16x32_bf16 v[26:29], v[158:161], v[192:195], v[26:29]
	v_mfma_f32_16x16x32_bf16 v[22:25], v[166:169], v[192:195], v[22:25]
	v_mfma_f32_16x16x32_bf16 v[18:21], v[158:161], v[200:203], v[18:21]
	v_mfma_f32_16x16x32_bf16 v[14:17], v[166:169], v[200:203], v[14:17]
	v_mfma_f32_16x16x32_bf16 v[10:13], v[158:161], v[210:213], v[10:13]
	v_mfma_f32_16x16x32_bf16 v[6:9], v[166:169], v[210:213], v[6:9]
	v_mfma_f32_16x16x32_bf16 v[34:37], v[162:165], v[188:191], v[34:37]
	v_mfma_f32_16x16x32_bf16 v[30:33], v[180:183], v[188:191], v[30:33]
	v_mfma_f32_16x16x32_bf16 v[26:29], v[162:165], v[196:199], v[26:29]
	v_mfma_f32_16x16x32_bf16 v[22:25], v[180:183], v[196:199], v[22:25]
	v_mfma_f32_16x16x32_bf16 v[18:21], v[162:165], v[204:207], v[18:21]
	v_mfma_f32_16x16x32_bf16 v[14:17], v[180:183], v[204:207], v[14:17]
	v_mfma_f32_16x16x32_bf16 v[10:13], v[162:165], v[214:217], v[10:13]
	v_mfma_f32_16x16x32_bf16 v[6:9], v[180:183], v[214:217], v[6:9]
	s_setprio 2
	s_barrier
	s_add_i32 s16, 0, 0x18000
	v_add_u32_e32 v2, s16, v173
	s_add_i32 s17, 0, 0x1c000
	ds_read_b128 v[142:145], v2
	ds_read_b128 v[146:149], v2 offset:1024
	ds_read_b128 v[150:153], v2 offset:2048
	ds_read_b128 v[154:157], v2 offset:3072
	v_add_u32_e32 v2, s17, v173
	ds_read_b128 v[158:161], v2
	ds_read_b128 v[162:165], v2 offset:1024
	ds_read_b128 v[166:169], v2 offset:2048
	ds_read_b128 v[180:183], v2 offset:3072
	s_add_u32 s14, s14, s23
	s_addc_u32 s15, s15, s22
	s_mov_b32 m0, s57
	ds_read_b128 v[184:187], v176 offset:32768
	ds_read_b128 v[188:191], v176 offset:33792
	ds_read_b128 v[192:195], v176 offset:34816
	ds_read_b128 v[196:199], v176 offset:35840
	ds_read_b128 v[200:203], v176 offset:36864
	ds_read_b128 v[204:207], v176 offset:37888
	ds_read_b128 v[210:213], v176 offset:38912
	ds_read_b128 v[214:217], v176 offset:39936
	global_load_lds_dwordx4 v222, s[14:15]
	s_mov_b32 m0, s0
	s_nop 0
	global_load_lds_dwordx4 v230, s[14:15]
	s_waitcnt vmcnt(8)
	s_waitcnt lgkmcnt(0)
	s_barrier
	s_setprio 1
	s_waitcnt lgkmcnt(0)
	v_mfma_f32_16x16x32_bf16 v[130:133], v[142:145], v[184:187], v[130:133]
	v_mfma_f32_16x16x32_bf16 v[126:129], v[150:153], v[184:187], v[126:129]
	v_mfma_f32_16x16x32_bf16 v[122:125], v[142:145], v[192:195], v[122:125]
	v_mfma_f32_16x16x32_bf16 v[118:121], v[150:153], v[192:195], v[118:121]
	v_mfma_f32_16x16x32_bf16 v[114:117], v[142:145], v[200:203], v[114:117]
	v_mfma_f32_16x16x32_bf16 v[110:113], v[150:153], v[200:203], v[110:113]
	v_mfma_f32_16x16x32_bf16 v[106:109], v[142:145], v[210:213], v[106:109]
	v_mfma_f32_16x16x32_bf16 v[102:105], v[150:153], v[210:213], v[102:105]
	v_mfma_f32_16x16x32_bf16 v[130:133], v[146:149], v[188:191], v[130:133]
	v_mfma_f32_16x16x32_bf16 v[126:129], v[154:157], v[188:191], v[126:129]
	v_mfma_f32_16x16x32_bf16 v[122:125], v[146:149], v[196:199], v[122:125]
	v_mfma_f32_16x16x32_bf16 v[118:121], v[154:157], v[196:199], v[118:121]
	v_mfma_f32_16x16x32_bf16 v[114:117], v[146:149], v[204:207], v[114:117]
	v_mfma_f32_16x16x32_bf16 v[110:113], v[154:157], v[204:207], v[110:113]
	v_mfma_f32_16x16x32_bf16 v[106:109], v[146:149], v[214:217], v[106:109]
	v_mfma_f32_16x16x32_bf16 v[102:105], v[154:157], v[214:217], v[102:105]
	s_setprio 0
	s_setprio 1
	v_mfma_f32_16x16x32_bf16 v[98:101], v[158:161], v[184:187], v[98:101]
	v_mfma_f32_16x16x32_bf16 v[94:97], v[166:169], v[184:187], v[94:97]
	v_mfma_f32_16x16x32_bf16 v[90:93], v[158:161], v[192:195], v[90:93]
	v_mfma_f32_16x16x32_bf16 v[86:89], v[166:169], v[192:195], v[86:89]
	v_mfma_f32_16x16x32_bf16 v[82:85], v[158:161], v[200:203], v[82:85]
	v_mfma_f32_16x16x32_bf16 v[78:81], v[166:169], v[200:203], v[78:81]
	v_mfma_f32_16x16x32_bf16 v[74:77], v[158:161], v[210:213], v[74:77]
	v_mfma_f32_16x16x32_bf16 v[70:73], v[166:169], v[210:213], v[70:73]
	v_mfma_f32_16x16x32_bf16 v[98:101], v[162:165], v[188:191], v[98:101]
	v_mfma_f32_16x16x32_bf16 v[94:97], v[180:183], v[188:191], v[94:97]
	v_mfma_f32_16x16x32_bf16 v[90:93], v[162:165], v[196:199], v[90:93]
	v_mfma_f32_16x16x32_bf16 v[86:89], v[180:183], v[196:199], v[86:89]
	v_mfma_f32_16x16x32_bf16 v[82:85], v[162:165], v[204:207], v[82:85]
	v_mfma_f32_16x16x32_bf16 v[78:81], v[180:183], v[204:207], v[78:81]
	v_mfma_f32_16x16x32_bf16 v[74:77], v[162:165], v[214:217], v[74:77]
	v_mfma_f32_16x16x32_bf16 v[70:73], v[180:183], v[214:217], v[70:73]
	s_setprio 2
	s_barrier
	s_add_i32 s14, s16, s5
	v_lshl_add_u64 v[220:221], v[220:221], 0, s[90:91]
	s_mov_b32 m0, s14
	ds_read_b128 v[184:187], v176 offset:49152
	ds_read_b128 v[188:191], v176 offset:50176
	ds_read_b128 v[192:195], v176 offset:51200
	ds_read_b128 v[196:199], v176 offset:52224
	ds_read_b128 v[200:203], v176 offset:53248
	ds_read_b128 v[204:207], v176 offset:54272
	ds_read_b128 v[210:213], v176 offset:55296
	ds_read_b128 v[214:217], v176 offset:56320
	global_load_lds_dwordx4 v[220:221], off
	v_lshl_add_u64 v[220:221], v[224:225], 0, s[90:91]
	s_add_i32 m0, s14, 0x2000
	s_add_i32 s14, s17, s5
	global_load_lds_dwordx4 v[220:221], off
	v_lshl_add_u64 v[220:221], v[226:227], 0, s[90:91]
	s_mov_b32 m0, s14
	v_lshl_add_u64 v[218:219], v[218:219], 0, s[90:91]
	global_load_lds_dwordx4 v[220:221], off
	s_add_i32 m0, s14, 0x2000
	s_nop 0
	global_load_lds_dwordx4 v[218:219], off
	v_lshl_add_u64 v[218:219], v[228:229], 0, s[90:91]
	s_mov_b32 m0, s43
	s_nop 0
	global_load_lds_dwordx4 v[218:219], off
	v_lshl_add_u64 v[218:219], v[232:233], 0, s[90:91]
	s_mov_b32 m0, s76
	s_nop 0
	global_load_lds_dwordx4 v[218:219], off
	s_waitcnt vmcnt(8)
	s_waitcnt lgkmcnt(0)
	s_barrier
	s_setprio 1
	s_waitcnt lgkmcnt(0)
	v_mfma_f32_16x16x32_bf16 v[66:69], v[142:145], v[184:187], v[66:69]
	v_mfma_f32_16x16x32_bf16 v[62:65], v[150:153], v[184:187], v[62:65]
	v_mfma_f32_16x16x32_bf16 v[58:61], v[142:145], v[192:195], v[58:61]
	v_mfma_f32_16x16x32_bf16 v[54:57], v[150:153], v[192:195], v[54:57]
	v_mfma_f32_16x16x32_bf16 v[50:53], v[142:145], v[200:203], v[50:53]
	v_mfma_f32_16x16x32_bf16 v[46:49], v[150:153], v[200:203], v[46:49]
	v_mfma_f32_16x16x32_bf16 v[42:45], v[142:145], v[210:213], v[42:45]
	v_mfma_f32_16x16x32_bf16 v[38:41], v[150:153], v[210:213], v[38:41]
	v_mfma_f32_16x16x32_bf16 v[66:69], v[146:149], v[188:191], v[66:69]
	v_mfma_f32_16x16x32_bf16 v[62:65], v[154:157], v[188:191], v[62:65]
	v_mfma_f32_16x16x32_bf16 v[58:61], v[146:149], v[196:199], v[58:61]
	v_mfma_f32_16x16x32_bf16 v[54:57], v[154:157], v[196:199], v[54:57]
	v_mfma_f32_16x16x32_bf16 v[50:53], v[146:149], v[204:207], v[50:53]
	v_mfma_f32_16x16x32_bf16 v[46:49], v[154:157], v[204:207], v[46:49]
	v_mfma_f32_16x16x32_bf16 v[42:45], v[146:149], v[214:217], v[42:45]
	v_mfma_f32_16x16x32_bf16 v[38:41], v[154:157], v[214:217], v[38:41]
	s_setprio 0
	s_setprio 1
	v_mfma_f32_16x16x32_bf16 v[34:37], v[158:161], v[184:187], v[34:37]
	v_mfma_f32_16x16x32_bf16 v[30:33], v[166:169], v[184:187], v[30:33]
	v_mfma_f32_16x16x32_bf16 v[26:29], v[158:161], v[192:195], v[26:29]
	v_mfma_f32_16x16x32_bf16 v[22:25], v[166:169], v[192:195], v[22:25]
	v_mfma_f32_16x16x32_bf16 v[18:21], v[158:161], v[200:203], v[18:21]
	v_mfma_f32_16x16x32_bf16 v[14:17], v[166:169], v[200:203], v[14:17]
	v_mfma_f32_16x16x32_bf16 v[10:13], v[158:161], v[210:213], v[10:13]
	v_mfma_f32_16x16x32_bf16 v[6:9], v[166:169], v[210:213], v[6:9]
	v_mfma_f32_16x16x32_bf16 v[34:37], v[162:165], v[188:191], v[34:37]
	v_mfma_f32_16x16x32_bf16 v[30:33], v[180:183], v[188:191], v[30:33]
	v_mfma_f32_16x16x32_bf16 v[26:29], v[162:165], v[196:199], v[26:29]
	v_mfma_f32_16x16x32_bf16 v[22:25], v[180:183], v[196:199], v[22:25]
	v_mfma_f32_16x16x32_bf16 v[18:21], v[162:165], v[204:207], v[18:21]
	v_mfma_f32_16x16x32_bf16 v[14:17], v[180:183], v[204:207], v[14:17]
	v_mfma_f32_16x16x32_bf16 v[10:13], v[162:165], v[214:217], v[10:13]
	v_mfma_f32_16x16x32_bf16 v[6:9], v[180:183], v[214:217], v[6:9]
	s_setprio 2
	s_barrier
	s_add_u32 s19, s19, 0x100
	s_addc_u32 s20, s20, 0
	s_add_u32 s12, s12, 0x100
	s_addc_u32 s13, s13, 0
	s_cmp_ge_i32 s21, s27
	s_mov_b32 s14, s21
	s_cbranch_scc0 .LBB0_341

.LBB0_626:
	ds_read_b128 v[130:133], v170
	ds_read_b128 v[150:153], v170 offset:1024
	ds_read_b128 v[154:157], v170 offset:2048
	ds_read_b128 v[158:161], v170 offset:3072
	ds_read_b128 v[162:165], v171
	ds_read_b128 v[174:177], v171 offset:1024
	ds_read_b128 v[178:181], v171 offset:2048
	ds_read_b128 v[182:185], v171 offset:3072
	s_add_i32 s46, s44, 2
	s_add_u32 s47, s0, 0x80
	s_addc_u32 s45, s1, 0
	s_cmp_eq_u32 s80, s44
	s_cselect_b32 s44, s40, s47
	s_cselect_b32 s45, s41, s45
	s_cselect_b32 vcc_hi, s43, s96
	s_cselect_b32 vcc_lo, s42, s95
	v_lshl_add_u64 v[166:167], s[0:1], 0, v[146:147]
	s_add_i32 m0, s56, 0xc000
	ds_read_b128 v[186:189], v172
	ds_read_b128 v[190:193], v172 offset:1024
	ds_read_b128 v[194:197], v172 offset:2048
	ds_read_b128 v[198:201], v172 offset:3072
	ds_read_b128 v[202:205], v172 offset:4096
	ds_read_b128 v[210:213], v172 offset:5120
	ds_read_b128 v[214:217], v172 offset:6144
	ds_read_b128 v[218:221], v172 offset:7168
	global_load_lds_dwordx4 v[166:167], off
	v_lshl_add_u64 v[166:167], s[0:1], 0, v[144:145]
	s_add_i32 m0, s56, 0xe000
	s_nop 0
	global_load_lds_dwordx4 v[166:167], off
	s_waitcnt vmcnt(8)
	s_waitcnt lgkmcnt(0)
	s_barrier
	s_setprio 1
	s_waitcnt lgkmcnt(0)
	v_mfma_f32_16x16x32_bf16 v[122:125], v[130:133], v[186:189], v[122:125]
	v_mfma_f32_16x16x32_bf16 v[126:129], v[154:157], v[186:189], v[126:129]
	v_mfma_f32_16x16x32_bf16 v[110:113], v[130:133], v[194:197], v[110:113]
	v_mfma_f32_16x16x32_bf16 v[106:109], v[154:157], v[194:197], v[106:109]
	v_mfma_f32_16x16x32_bf16 v[94:97], v[130:133], v[202:205], v[94:97]
	v_mfma_f32_16x16x32_bf16 v[90:93], v[154:157], v[202:205], v[90:93]
	v_mfma_f32_16x16x32_bf16 v[78:81], v[130:133], v[214:217], v[78:81]
	v_mfma_f32_16x16x32_bf16 v[74:77], v[154:157], v[214:217], v[74:77]
	v_mfma_f32_16x16x32_bf16 v[122:125], v[150:153], v[190:193], v[122:125]
	v_mfma_f32_16x16x32_bf16 v[126:129], v[158:161], v[190:193], v[126:129]
	v_mfma_f32_16x16x32_bf16 v[110:113], v[150:153], v[198:201], v[110:113]
	v_mfma_f32_16x16x32_bf16 v[106:109], v[158:161], v[198:201], v[106:109]
	v_mfma_f32_16x16x32_bf16 v[94:97], v[150:153], v[210:213], v[94:97]
	v_mfma_f32_16x16x32_bf16 v[90:93], v[158:161], v[210:213], v[90:93]
	v_mfma_f32_16x16x32_bf16 v[78:81], v[150:153], v[218:221], v[78:81]
	v_mfma_f32_16x16x32_bf16 v[74:77], v[158:161], v[218:221], v[74:77]
	s_setprio 0
	s_setprio 1
	v_mfma_f32_16x16x32_bf16 v[118:121], v[162:165], v[186:189], v[118:121]
	v_mfma_f32_16x16x32_bf16 v[114:117], v[178:181], v[186:189], v[114:117]
	v_mfma_f32_16x16x32_bf16 v[102:105], v[162:165], v[194:197], v[102:105]
	v_mfma_f32_16x16x32_bf16 v[98:101], v[178:181], v[194:197], v[98:101]
	v_mfma_f32_16x16x32_bf16 v[86:89], v[162:165], v[202:205], v[86:89]
	v_mfma_f32_16x16x32_bf16 v[82:85], v[178:181], v[202:205], v[82:85]
	v_mfma_f32_16x16x32_bf16 v[70:73], v[162:165], v[214:217], v[70:73]
	v_mfma_f32_16x16x32_bf16 v[66:69], v[178:181], v[214:217], v[66:69]
	v_mfma_f32_16x16x32_bf16 v[118:121], v[174:177], v[190:193], v[118:121]
	v_mfma_f32_16x16x32_bf16 v[114:117], v[182:185], v[190:193], v[114:117]
	v_mfma_f32_16x16x32_bf16 v[102:105], v[174:177], v[198:201], v[102:105]
	v_mfma_f32_16x16x32_bf16 v[98:101], v[182:185], v[198:201], v[98:101]
	v_mfma_f32_16x16x32_bf16 v[86:89], v[174:177], v[210:213], v[86:89]
	v_mfma_f32_16x16x32_bf16 v[82:85], v[182:185], v[210:213], v[82:85]
	v_mfma_f32_16x16x32_bf16 v[70:73], v[174:177], v[218:221], v[70:73]
	v_mfma_f32_16x16x32_bf16 v[66:69], v[182:185], v[218:221], v[66:69]
	s_setprio 2
	s_barrier
	s_add_i32 s47, s86, s55
	v_lshl_add_u64 v[166:167], vcc, 0, v[136:137]
	s_mov_b32 m0, s47
	ds_read_b128 v[186:189], v172 offset:16384
	ds_read_b128 v[190:193], v172 offset:17408
	ds_read_b128 v[194:197], v172 offset:18432
	ds_read_b128 v[198:201], v172 offset:19456
	ds_read_b128 v[202:205], v172 offset:20480
	ds_read_b128 v[210:213], v172 offset:21504
	ds_read_b128 v[214:217], v172 offset:22528
	ds_read_b128 v[218:221], v172 offset:23552
	global_load_lds_dwordx4 v[166:167], off
	s_add_i32 m0, s47, 0x2000
	v_lshl_add_u64 v[206:207], vcc, 0, v[138:139]
	s_add_u32 vcc_lo, vcc_lo, s16
	s_addc_u32 vcc_hi, vcc_hi, s17
	s_add_i32 s47, s87, s55
	global_load_lds_dwordx4 v[206:207], off
	v_lshl_add_u64 v[222:223], vcc, 0, v[136:137]
	s_mov_b32 m0, s47
	v_lshl_add_u64 v[224:225], vcc, 0, v[138:139]
	global_load_lds_dwordx4 v[222:223], off
	s_add_i32 m0, s47, 0x2000
	v_lshl_add_u64 v[226:227], s[44:45], 0, v[140:141]
	global_load_lds_dwordx4 v[224:225], off
	s_mov_b32 m0, s56
	v_lshl_add_u64 v[228:229], s[44:45], 0, v[142:143]
	global_load_lds_dwordx4 v[226:227], off
	s_mov_b32 m0, s57
	s_nop 0
	global_load_lds_dwordx4 v[228:229], off
	s_waitcnt vmcnt(8)
	s_waitcnt lgkmcnt(0)
	s_barrier
	s_setprio 1
	s_waitcnt lgkmcnt(0)
	v_mfma_f32_16x16x32_bf16 v[62:65], v[130:133], v[186:189], v[62:65]
	v_mfma_f32_16x16x32_bf16 v[58:61], v[154:157], v[186:189], v[58:61]
	v_mfma_f32_16x16x32_bf16 v[46:49], v[130:133], v[194:197], v[46:49]
	v_mfma_f32_16x16x32_bf16 v[42:45], v[154:157], v[194:197], v[42:45]
	v_mfma_f32_16x16x32_bf16 v[30:33], v[130:133], v[202:205], v[30:33]
	v_mfma_f32_16x16x32_bf16 v[26:29], v[154:157], v[202:205], v[26:29]
	v_mfma_f32_16x16x32_bf16 v[14:17], v[130:133], v[214:217], v[14:17]
	v_mfma_f32_16x16x32_bf16 v[10:13], v[154:157], v[214:217], v[10:13]
	v_mfma_f32_16x16x32_bf16 v[62:65], v[150:153], v[190:193], v[62:65]
	v_mfma_f32_16x16x32_bf16 v[58:61], v[158:161], v[190:193], v[58:61]
	v_mfma_f32_16x16x32_bf16 v[46:49], v[150:153], v[198:201], v[46:49]
	v_mfma_f32_16x16x32_bf16 v[42:45], v[158:161], v[198:201], v[42:45]
	v_mfma_f32_16x16x32_bf16 v[30:33], v[150:153], v[210:213], v[30:33]
	v_mfma_f32_16x16x32_bf16 v[26:29], v[158:161], v[210:213], v[26:29]
	v_mfma_f32_16x16x32_bf16 v[14:17], v[150:153], v[218:221], v[14:17]
	v_mfma_f32_16x16x32_bf16 v[10:13], v[158:161], v[218:221], v[10:13]
	s_setprio 0
	s_setprio 1
	v_mfma_f32_16x16x32_bf16 v[54:57], v[162:165], v[186:189], v[54:57]
	v_mfma_f32_16x16x32_bf16 v[50:53], v[178:181], v[186:189], v[50:53]
	v_mfma_f32_16x16x32_bf16 v[38:41], v[162:165], v[194:197], v[38:41]
	v_mfma_f32_16x16x32_bf16 v[34:37], v[178:181], v[194:197], v[34:37]
	v_mfma_f32_16x16x32_bf16 v[22:25], v[162:165], v[202:205], v[22:25]
	v_mfma_f32_16x16x32_bf16 v[18:21], v[178:181], v[202:205], v[18:21]
	v_mfma_f32_16x16x32_bf16 v[6:9], v[162:165], v[214:217], v[6:9]
	v_mfma_f32_16x16x32_bf16 v[2:5], v[178:181], v[214:217], v[2:5]
	v_mfma_f32_16x16x32_bf16 v[54:57], v[174:177], v[190:193], v[54:57]
	v_mfma_f32_16x16x32_bf16 v[50:53], v[182:185], v[190:193], v[50:53]
	v_mfma_f32_16x16x32_bf16 v[38:41], v[174:177], v[198:201], v[38:41]
	v_mfma_f32_16x16x32_bf16 v[34:37], v[182:185], v[198:201], v[34:37]
	v_mfma_f32_16x16x32_bf16 v[22:25], v[174:177], v[210:213], v[22:25]
	v_mfma_f32_16x16x32_bf16 v[18:21], v[182:185], v[210:213], v[18:21]
	v_mfma_f32_16x16x32_bf16 v[6:9], v[174:177], v[218:221], v[6:9]
	v_mfma_f32_16x16x32_bf16 v[2:5], v[182:185], v[218:221], v[2:5]
	s_setprio 2
	s_barrier
	s_add_i32 s47, 0, 0x18000
	s_add_i32 vcc_lo, 0, 0x1c000
	v_add_u32_e32 v158, s47, v169
	v_add_u32_e32 v182, vcc_lo, v169
	ds_read_b128 v[130:133], v158
	ds_read_b128 v[150:153], v158 offset:1024
	ds_read_b128 v[154:157], v158 offset:2048
	ds_read_b128 v[158:161], v158 offset:3072
	ds_read_b128 v[162:165], v182
	ds_read_b128 v[174:177], v182 offset:1024
	ds_read_b128 v[178:181], v182 offset:2048
	ds_read_b128 v[182:185], v182 offset:3072
	s_add_u32 s44, s44, s16
	s_addc_u32 s45, s45, s17
	s_mov_b32 m0, s58
	v_lshl_add_u64 v[230:231], s[44:45], 0, v[140:141]
	ds_read_b128 v[186:189], v172 offset:32768
	ds_read_b128 v[190:193], v172 offset:33792
	ds_read_b128 v[194:197], v172 offset:34816
	ds_read_b128 v[198:201], v172 offset:35840
	ds_read_b128 v[202:205], v172 offset:36864
	ds_read_b128 v[210:213], v172 offset:37888
	ds_read_b128 v[214:217], v172 offset:38912
	ds_read_b128 v[218:221], v172 offset:39936
	global_load_lds_dwordx4 v[230:231], off
	v_lshl_add_u64 v[230:231], s[44:45], 0, v[142:143]
	s_mov_b32 m0, s59
	s_nop 0
	global_load_lds_dwordx4 v[230:231], off
	s_waitcnt vmcnt(8)
	s_waitcnt lgkmcnt(0)
	s_barrier
	s_setprio 1
	s_waitcnt lgkmcnt(0)
	v_mfma_f32_16x16x32_bf16 v[122:125], v[130:133], v[186:189], v[122:125]
	v_mfma_f32_16x16x32_bf16 v[126:129], v[154:157], v[186:189], v[126:129]
	v_mfma_f32_16x16x32_bf16 v[110:113], v[130:133], v[194:197], v[110:113]
	v_mfma_f32_16x16x32_bf16 v[106:109], v[154:157], v[194:197], v[106:109]
	v_mfma_f32_16x16x32_bf16 v[94:97], v[130:133], v[202:205], v[94:97]
	v_mfma_f32_16x16x32_bf16 v[90:93], v[154:157], v[202:205], v[90:93]
	v_mfma_f32_16x16x32_bf16 v[78:81], v[130:133], v[214:217], v[78:81]
	v_mfma_f32_16x16x32_bf16 v[74:77], v[154:157], v[214:217], v[74:77]
	v_mfma_f32_16x16x32_bf16 v[122:125], v[150:153], v[190:193], v[122:125]
	v_mfma_f32_16x16x32_bf16 v[126:129], v[158:161], v[190:193], v[126:129]
	v_mfma_f32_16x16x32_bf16 v[110:113], v[150:153], v[198:201], v[110:113]
	v_mfma_f32_16x16x32_bf16 v[106:109], v[158:161], v[198:201], v[106:109]
	v_mfma_f32_16x16x32_bf16 v[94:97], v[150:153], v[210:213], v[94:97]
	v_mfma_f32_16x16x32_bf16 v[90:93], v[158:161], v[210:213], v[90:93]
	v_mfma_f32_16x16x32_bf16 v[78:81], v[150:153], v[218:221], v[78:81]
	v_mfma_f32_16x16x32_bf16 v[74:77], v[158:161], v[218:221], v[74:77]
	s_setprio 0
	s_setprio 1
	v_mfma_f32_16x16x32_bf16 v[118:121], v[162:165], v[186:189], v[118:121]
	v_mfma_f32_16x16x32_bf16 v[114:117], v[178:181], v[186:189], v[114:117]
	v_mfma_f32_16x16x32_bf16 v[102:105], v[162:165], v[194:197], v[102:105]
	v_mfma_f32_16x16x32_bf16 v[98:101], v[178:181], v[194:197], v[98:101]
	v_mfma_f32_16x16x32_bf16 v[86:89], v[162:165], v[202:205], v[86:89]
	v_mfma_f32_16x16x32_bf16 v[82:85], v[178:181], v[202:205], v[82:85]
	v_mfma_f32_16x16x32_bf16 v[70:73], v[162:165], v[214:217], v[70:73]
	v_mfma_f32_16x16x32_bf16 v[66:69], v[178:181], v[214:217], v[66:69]
	v_mfma_f32_16x16x32_bf16 v[118:121], v[174:177], v[190:193], v[118:121]
	v_mfma_f32_16x16x32_bf16 v[114:117], v[182:185], v[190:193], v[114:117]
	v_mfma_f32_16x16x32_bf16 v[102:105], v[174:177], v[198:201], v[102:105]
	v_mfma_f32_16x16x32_bf16 v[98:101], v[182:185], v[198:201], v[98:101]
	v_mfma_f32_16x16x32_bf16 v[86:89], v[174:177], v[210:213], v[86:89]
	v_mfma_f32_16x16x32_bf16 v[82:85], v[182:185], v[210:213], v[82:85]
	v_mfma_f32_16x16x32_bf16 v[70:73], v[174:177], v[218:221], v[70:73]
	v_mfma_f32_16x16x32_bf16 v[66:69], v[182:185], v[218:221], v[66:69]
	s_setprio 2
	s_barrier
	s_add_i32 s44, s47, s55
	v_lshl_add_u64 v[166:167], v[166:167], 0, s[24:25]
	s_mov_b32 m0, s44
	ds_read_b128 v[186:189], v172 offset:49152
	ds_read_b128 v[190:193], v172 offset:50176
	ds_read_b128 v[194:197], v172 offset:51200
	ds_read_b128 v[198:201], v172 offset:52224
	ds_read_b128 v[202:205], v172 offset:53248
	ds_read_b128 v[210:213], v172 offset:54272
	ds_read_b128 v[214:217], v172 offset:55296
	ds_read_b128 v[218:221], v172 offset:56320
	global_load_lds_dwordx4 v[166:167], off
	v_lshl_add_u64 v[166:167], v[206:207], 0, s[24:25]
	s_add_i32 m0, s44, 0x2000
	s_add_i32 s44, vcc_lo, s55
	global_load_lds_dwordx4 v[166:167], off
	v_lshl_add_u64 v[166:167], v[222:223], 0, s[24:25]
	s_mov_b32 m0, s44
	s_nop 0
	global_load_lds_dwordx4 v[166:167], off
	v_lshl_add_u64 v[166:167], v[224:225], 0, s[24:25]
	s_add_i32 m0, s44, 0x2000
	s_nop 0
	global_load_lds_dwordx4 v[166:167], off
	v_lshl_add_u64 v[166:167], v[226:227], 0, s[24:25]
	s_mov_b32 m0, s63
	s_nop 0
	global_load_lds_dwordx4 v[166:167], off
	v_lshl_add_u64 v[166:167], v[228:229], 0, s[24:25]
	s_mov_b32 m0, s64
	s_nop 0
	global_load_lds_dwordx4 v[166:167], off
	s_waitcnt vmcnt(8)
	s_waitcnt lgkmcnt(0)
	s_barrier
	s_setprio 1
	s_waitcnt lgkmcnt(0)
	v_mfma_f32_16x16x32_bf16 v[62:65], v[130:133], v[186:189], v[62:65]
	v_mfma_f32_16x16x32_bf16 v[58:61], v[154:157], v[186:189], v[58:61]
	v_mfma_f32_16x16x32_bf16 v[46:49], v[130:133], v[194:197], v[46:49]
	v_mfma_f32_16x16x32_bf16 v[42:45], v[154:157], v[194:197], v[42:45]
	v_mfma_f32_16x16x32_bf16 v[30:33], v[130:133], v[202:205], v[30:33]
	v_mfma_f32_16x16x32_bf16 v[26:29], v[154:157], v[202:205], v[26:29]
	v_mfma_f32_16x16x32_bf16 v[14:17], v[130:133], v[214:217], v[14:17]
	v_mfma_f32_16x16x32_bf16 v[10:13], v[154:157], v[214:217], v[10:13]
	v_mfma_f32_16x16x32_bf16 v[62:65], v[150:153], v[190:193], v[62:65]
	v_mfma_f32_16x16x32_bf16 v[58:61], v[158:161], v[190:193], v[58:61]
	v_mfma_f32_16x16x32_bf16 v[46:49], v[150:153], v[198:201], v[46:49]
	v_mfma_f32_16x16x32_bf16 v[42:45], v[158:161], v[198:201], v[42:45]
	v_mfma_f32_16x16x32_bf16 v[30:33], v[150:153], v[210:213], v[30:33]
	v_mfma_f32_16x16x32_bf16 v[26:29], v[158:161], v[210:213], v[26:29]
	v_mfma_f32_16x16x32_bf16 v[14:17], v[150:153], v[218:221], v[14:17]
	v_mfma_f32_16x16x32_bf16 v[10:13], v[158:161], v[218:221], v[10:13]
	s_setprio 0
	s_setprio 1
	v_mfma_f32_16x16x32_bf16 v[54:57], v[162:165], v[186:189], v[54:57]
	v_mfma_f32_16x16x32_bf16 v[50:53], v[178:181], v[186:189], v[50:53]
	v_mfma_f32_16x16x32_bf16 v[38:41], v[162:165], v[194:197], v[38:41]
	v_mfma_f32_16x16x32_bf16 v[34:37], v[178:181], v[194:197], v[34:37]
	v_mfma_f32_16x16x32_bf16 v[22:25], v[162:165], v[202:205], v[22:25]
	v_mfma_f32_16x16x32_bf16 v[18:21], v[178:181], v[202:205], v[18:21]
	v_mfma_f32_16x16x32_bf16 v[6:9], v[162:165], v[214:217], v[6:9]
	v_mfma_f32_16x16x32_bf16 v[2:5], v[178:181], v[214:217], v[2:5]
	v_mfma_f32_16x16x32_bf16 v[54:57], v[174:177], v[190:193], v[54:57]
	v_mfma_f32_16x16x32_bf16 v[50:53], v[182:185], v[190:193], v[50:53]
	v_mfma_f32_16x16x32_bf16 v[38:41], v[174:177], v[198:201], v[38:41]
	v_mfma_f32_16x16x32_bf16 v[34:37], v[182:185], v[198:201], v[34:37]
	v_mfma_f32_16x16x32_bf16 v[22:25], v[174:177], v[210:213], v[22:25]
	v_mfma_f32_16x16x32_bf16 v[18:21], v[182:185], v[210:213], v[18:21]
	v_mfma_f32_16x16x32_bf16 v[6:9], v[174:177], v[218:221], v[6:9]
	v_mfma_f32_16x16x32_bf16 v[2:5], v[182:185], v[218:221], v[2:5]
	s_setprio 2
	s_barrier
	s_add_u32 s95, s95, 0x100
	s_addc_u32 s96, s96, 0
	s_add_u32 s0, s0, 0x100
	s_addc_u32 s1, s1, 0
	s_cmp_ge_i32 s46, s65
	s_mov_b32 s44, s46
	s_cbranch_scc0 .LBB0_626

.LBB0_1087:
	v_add_u32_e32 v149, s71, v146
	ds_read_b128 v[142:145], v149
	ds_read_b128 v[152:155], v149 offset:1024
	ds_read_b128 v[156:159], v149 offset:2048
	ds_read_b128 v[160:163], v149 offset:3072
	v_add_u32_e32 v149, s72, v146
	ds_read_b128 v[164:167], v149
	ds_read_b128 v[168:171], v149 offset:1024
	ds_read_b128 v[172:175], v149 offset:2048
	ds_read_b128 v[176:179], v149 offset:3072
	s_add_i32 s42, s40, 2
	s_add_u32 s43, s4, 0x80
	s_addc_u32 s41, s5, 0
	s_cmp_eq_u32 s58, s40
	s_cselect_b32 s40, s36, s43
	s_cselect_b32 s41, s37, s41
	s_cselect_b32 s81, s39, s78
	s_cselect_b32 s80, s38, s77
	v_lshl_add_u64 v[214:215], s[4:5], 0, v[140:141]
	s_add_i32 m0, s48, 0xc000
	ds_read_b128 v[180:183], v147
	ds_read_b128 v[184:187], v147 offset:1024
	ds_read_b128 v[188:191], v147 offset:2048
	ds_read_b128 v[192:195], v147 offset:3072
	ds_read_b128 v[196:199], v147 offset:4096
	ds_read_b128 v[200:203], v147 offset:5120
	ds_read_b128 v[204:207], v147 offset:6144
	ds_read_b128 v[210:213], v147 offset:7168
	global_load_lds_dwordx4 v[214:215], off
	v_lshl_add_u64 v[214:215], s[4:5], 0, v[138:139]
	s_add_i32 m0, s48, 0xe000
	s_nop 0
	global_load_lds_dwordx4 v[214:215], off
	s_waitcnt vmcnt(8)
	s_waitcnt lgkmcnt(0)
	s_barrier
	s_setprio 1
	s_waitcnt lgkmcnt(0)
	v_mfma_f32_16x16x32_bf16 v[126:129], v[142:145], v[180:183], v[126:129]
	v_mfma_f32_16x16x32_bf16 v[122:125], v[156:159], v[180:183], v[122:125]
	v_mfma_f32_16x16x32_bf16 v[110:113], v[142:145], v[188:191], v[110:113]
	v_mfma_f32_16x16x32_bf16 v[106:109], v[156:159], v[188:191], v[106:109]
	v_mfma_f32_16x16x32_bf16 v[94:97], v[142:145], v[196:199], v[94:97]
	v_mfma_f32_16x16x32_bf16 v[90:93], v[156:159], v[196:199], v[90:93]
	v_mfma_f32_16x16x32_bf16 v[78:81], v[142:145], v[204:207], v[78:81]
	v_mfma_f32_16x16x32_bf16 v[74:77], v[156:159], v[204:207], v[74:77]
	v_mfma_f32_16x16x32_bf16 v[126:129], v[152:155], v[184:187], v[126:129]
	v_mfma_f32_16x16x32_bf16 v[122:125], v[160:163], v[184:187], v[122:125]
	v_mfma_f32_16x16x32_bf16 v[110:113], v[152:155], v[192:195], v[110:113]
	v_mfma_f32_16x16x32_bf16 v[106:109], v[160:163], v[192:195], v[106:109]
	v_mfma_f32_16x16x32_bf16 v[94:97], v[152:155], v[200:203], v[94:97]
	v_mfma_f32_16x16x32_bf16 v[90:93], v[160:163], v[200:203], v[90:93]
	v_mfma_f32_16x16x32_bf16 v[78:81], v[152:155], v[210:213], v[78:81]
	v_mfma_f32_16x16x32_bf16 v[74:77], v[160:163], v[210:213], v[74:77]
	s_setprio 0
	s_setprio 1
	v_mfma_f32_16x16x32_bf16 v[118:121], v[164:167], v[180:183], v[118:121]
	v_mfma_f32_16x16x32_bf16 v[114:117], v[172:175], v[180:183], v[114:117]
	v_mfma_f32_16x16x32_bf16 v[102:105], v[164:167], v[188:191], v[102:105]
	v_mfma_f32_16x16x32_bf16 v[98:101], v[172:175], v[188:191], v[98:101]
	v_mfma_f32_16x16x32_bf16 v[86:89], v[164:167], v[196:199], v[86:89]
	v_mfma_f32_16x16x32_bf16 v[82:85], v[172:175], v[196:199], v[82:85]
	v_mfma_f32_16x16x32_bf16 v[70:73], v[164:167], v[204:207], v[70:73]
	v_mfma_f32_16x16x32_bf16 v[66:69], v[172:175], v[204:207], v[66:69]
	v_mfma_f32_16x16x32_bf16 v[118:121], v[168:171], v[184:187], v[118:121]
	v_mfma_f32_16x16x32_bf16 v[114:117], v[176:179], v[184:187], v[114:117]
	v_mfma_f32_16x16x32_bf16 v[102:105], v[168:171], v[192:195], v[102:105]
	v_mfma_f32_16x16x32_bf16 v[98:101], v[176:179], v[192:195], v[98:101]
	v_mfma_f32_16x16x32_bf16 v[86:89], v[168:171], v[200:203], v[86:89]
	v_mfma_f32_16x16x32_bf16 v[82:85], v[176:179], v[200:203], v[82:85]
	v_mfma_f32_16x16x32_bf16 v[70:73], v[168:171], v[210:213], v[70:73]
	v_mfma_f32_16x16x32_bf16 v[66:69], v[176:179], v[210:213], v[66:69]
	s_setprio 2
	s_barrier
	s_add_i32 s43, s71, s45
	v_lshl_add_u64 v[214:215], s[80:81], 0, v[130:131]
	s_mov_b32 m0, s43
	ds_read_b128 v[180:183], v147 offset:16384
	ds_read_b128 v[184:187], v147 offset:17408
	ds_read_b128 v[188:191], v147 offset:18432
	ds_read_b128 v[192:195], v147 offset:19456
	ds_read_b128 v[196:199], v147 offset:20480
	ds_read_b128 v[200:203], v147 offset:21504
	ds_read_b128 v[204:207], v147 offset:22528
	ds_read_b128 v[210:213], v147 offset:23552
	global_load_lds_dwordx4 v[214:215], off
	s_add_i32 m0, s43, 0x2000
	v_lshl_add_u64 v[216:217], s[80:81], 0, v[132:133]
	s_add_u32 s80, s80, s12
	s_addc_u32 s81, s81, s13
	s_add_i32 s43, s72, s45
	global_load_lds_dwordx4 v[216:217], off
	v_lshl_add_u64 v[218:219], s[80:81], 0, v[130:131]
	s_mov_b32 m0, s43
	v_lshl_add_u64 v[220:221], s[80:81], 0, v[132:133]
	global_load_lds_dwordx4 v[218:219], off
	s_add_i32 m0, s43, 0x2000
	v_lshl_add_u64 v[222:223], s[40:41], 0, v[134:135]
	global_load_lds_dwordx4 v[220:221], off
	s_mov_b32 m0, s48
	v_lshl_add_u64 v[224:225], s[40:41], 0, v[136:137]
	global_load_lds_dwordx4 v[222:223], off
	s_mov_b32 m0, s49
	s_nop 0
	global_load_lds_dwordx4 v[224:225], off
	s_waitcnt vmcnt(8)
	s_waitcnt lgkmcnt(0)
	s_barrier
	s_setprio 1
	s_waitcnt lgkmcnt(0)
	v_mfma_f32_16x16x32_bf16 v[62:65], v[142:145], v[180:183], v[62:65]
	v_mfma_f32_16x16x32_bf16 v[58:61], v[156:159], v[180:183], v[58:61]
	v_mfma_f32_16x16x32_bf16 v[46:49], v[142:145], v[188:191], v[46:49]
	v_mfma_f32_16x16x32_bf16 v[42:45], v[156:159], v[188:191], v[42:45]
	v_mfma_f32_16x16x32_bf16 v[30:33], v[142:145], v[196:199], v[30:33]
	v_mfma_f32_16x16x32_bf16 v[26:29], v[156:159], v[196:199], v[26:29]
	v_mfma_f32_16x16x32_bf16 v[14:17], v[142:145], v[204:207], v[14:17]
	v_mfma_f32_16x16x32_bf16 v[10:13], v[156:159], v[204:207], v[10:13]
	v_mfma_f32_16x16x32_bf16 v[62:65], v[152:155], v[184:187], v[62:65]
	v_mfma_f32_16x16x32_bf16 v[58:61], v[160:163], v[184:187], v[58:61]
	v_mfma_f32_16x16x32_bf16 v[46:49], v[152:155], v[192:195], v[46:49]
	v_mfma_f32_16x16x32_bf16 v[42:45], v[160:163], v[192:195], v[42:45]
	v_mfma_f32_16x16x32_bf16 v[30:33], v[152:155], v[200:203], v[30:33]
	v_mfma_f32_16x16x32_bf16 v[26:29], v[160:163], v[200:203], v[26:29]
	v_mfma_f32_16x16x32_bf16 v[14:17], v[152:155], v[210:213], v[14:17]
	v_mfma_f32_16x16x32_bf16 v[10:13], v[160:163], v[210:213], v[10:13]
	s_setprio 0
	s_setprio 1
	v_mfma_f32_16x16x32_bf16 v[54:57], v[164:167], v[180:183], v[54:57]
	v_mfma_f32_16x16x32_bf16 v[50:53], v[172:175], v[180:183], v[50:53]
	v_mfma_f32_16x16x32_bf16 v[38:41], v[164:167], v[188:191], v[38:41]
	v_mfma_f32_16x16x32_bf16 v[34:37], v[172:175], v[188:191], v[34:37]
	v_mfma_f32_16x16x32_bf16 v[22:25], v[164:167], v[196:199], v[22:25]
	v_mfma_f32_16x16x32_bf16 v[18:21], v[172:175], v[196:199], v[18:21]
	v_mfma_f32_16x16x32_bf16 v[6:9], v[164:167], v[204:207], v[6:9]
	v_mfma_f32_16x16x32_bf16 v[2:5], v[172:175], v[204:207], v[2:5]
	v_mfma_f32_16x16x32_bf16 v[54:57], v[168:171], v[184:187], v[54:57]
	v_mfma_f32_16x16x32_bf16 v[50:53], v[176:179], v[184:187], v[50:53]
	v_mfma_f32_16x16x32_bf16 v[38:41], v[168:171], v[192:195], v[38:41]
	v_mfma_f32_16x16x32_bf16 v[34:37], v[176:179], v[192:195], v[34:37]
	v_mfma_f32_16x16x32_bf16 v[22:25], v[168:171], v[200:203], v[22:25]
	v_mfma_f32_16x16x32_bf16 v[18:21], v[176:179], v[200:203], v[18:21]
	v_mfma_f32_16x16x32_bf16 v[6:9], v[168:171], v[210:213], v[6:9]
	v_mfma_f32_16x16x32_bf16 v[2:5], v[176:179], v[210:213], v[2:5]
	s_setprio 2
	s_barrier
	s_add_i32 s43, 0, 0x18000
	v_add_u32_e32 v149, s43, v146
	s_add_i32 s79, 0, 0x1c000
	ds_read_b128 v[142:145], v149
	ds_read_b128 v[152:155], v149 offset:1024
	ds_read_b128 v[156:159], v149 offset:2048
	ds_read_b128 v[160:163], v149 offset:3072
	v_add_u32_e32 v149, s79, v146
	ds_read_b128 v[164:167], v149
	ds_read_b128 v[168:171], v149 offset:1024
	ds_read_b128 v[172:175], v149 offset:2048
	ds_read_b128 v[176:179], v149 offset:3072
	s_add_u32 s40, s40, s12
	s_addc_u32 s41, s41, s13
	s_mov_b32 m0, s50
	v_lshl_add_u64 v[226:227], s[40:41], 0, v[134:135]
	ds_read_b128 v[180:183], v147 offset:32768
	ds_read_b128 v[184:187], v147 offset:33792
	ds_read_b128 v[188:191], v147 offset:34816
	ds_read_b128 v[192:195], v147 offset:35840
	ds_read_b128 v[196:199], v147 offset:36864
	ds_read_b128 v[200:203], v147 offset:37888
	ds_read_b128 v[204:207], v147 offset:38912
	ds_read_b128 v[210:213], v147 offset:39936
	global_load_lds_dwordx4 v[226:227], off
	v_lshl_add_u64 v[226:227], s[40:41], 0, v[136:137]
	s_mov_b32 m0, s51
	s_nop 0
	global_load_lds_dwordx4 v[226:227], off
	s_waitcnt vmcnt(8)
	s_waitcnt lgkmcnt(0)
	s_barrier
	s_setprio 1
	s_waitcnt lgkmcnt(0)
	v_mfma_f32_16x16x32_bf16 v[126:129], v[142:145], v[180:183], v[126:129]
	v_mfma_f32_16x16x32_bf16 v[122:125], v[156:159], v[180:183], v[122:125]
	v_mfma_f32_16x16x32_bf16 v[110:113], v[142:145], v[188:191], v[110:113]
	v_mfma_f32_16x16x32_bf16 v[106:109], v[156:159], v[188:191], v[106:109]
	v_mfma_f32_16x16x32_bf16 v[94:97], v[142:145], v[196:199], v[94:97]
	v_mfma_f32_16x16x32_bf16 v[90:93], v[156:159], v[196:199], v[90:93]
	v_mfma_f32_16x16x32_bf16 v[78:81], v[142:145], v[204:207], v[78:81]
	v_mfma_f32_16x16x32_bf16 v[74:77], v[156:159], v[204:207], v[74:77]
	v_mfma_f32_16x16x32_bf16 v[126:129], v[152:155], v[184:187], v[126:129]
	v_mfma_f32_16x16x32_bf16 v[122:125], v[160:163], v[184:187], v[122:125]
	v_mfma_f32_16x16x32_bf16 v[110:113], v[152:155], v[192:195], v[110:113]
	v_mfma_f32_16x16x32_bf16 v[106:109], v[160:163], v[192:195], v[106:109]
	v_mfma_f32_16x16x32_bf16 v[94:97], v[152:155], v[200:203], v[94:97]
	v_mfma_f32_16x16x32_bf16 v[90:93], v[160:163], v[200:203], v[90:93]
	v_mfma_f32_16x16x32_bf16 v[78:81], v[152:155], v[210:213], v[78:81]
	v_mfma_f32_16x16x32_bf16 v[74:77], v[160:163], v[210:213], v[74:77]
	s_setprio 0
	s_setprio 1
	v_mfma_f32_16x16x32_bf16 v[118:121], v[164:167], v[180:183], v[118:121]
	v_mfma_f32_16x16x32_bf16 v[114:117], v[172:175], v[180:183], v[114:117]
	v_mfma_f32_16x16x32_bf16 v[102:105], v[164:167], v[188:191], v[102:105]
	v_mfma_f32_16x16x32_bf16 v[98:101], v[172:175], v[188:191], v[98:101]
	v_mfma_f32_16x16x32_bf16 v[86:89], v[164:167], v[196:199], v[86:89]
	v_mfma_f32_16x16x32_bf16 v[82:85], v[172:175], v[196:199], v[82:85]
	v_mfma_f32_16x16x32_bf16 v[70:73], v[164:167], v[204:207], v[70:73]
	v_mfma_f32_16x16x32_bf16 v[66:69], v[172:175], v[204:207], v[66:69]
	v_mfma_f32_16x16x32_bf16 v[118:121], v[168:171], v[184:187], v[118:121]
	v_mfma_f32_16x16x32_bf16 v[114:117], v[176:179], v[184:187], v[114:117]
	v_mfma_f32_16x16x32_bf16 v[102:105], v[168:171], v[192:195], v[102:105]
	v_mfma_f32_16x16x32_bf16 v[98:101], v[176:179], v[192:195], v[98:101]
	v_mfma_f32_16x16x32_bf16 v[86:89], v[168:171], v[200:203], v[86:89]
	v_mfma_f32_16x16x32_bf16 v[82:85], v[176:179], v[200:203], v[82:85]
	v_mfma_f32_16x16x32_bf16 v[70:73], v[168:171], v[210:213], v[70:73]
	v_mfma_f32_16x16x32_bf16 v[66:69], v[176:179], v[210:213], v[66:69]
	s_setprio 2
	s_barrier
	s_add_i32 s40, s43, s45
	v_lshl_add_u64 v[214:215], v[214:215], 0, s[20:21]
	s_mov_b32 m0, s40
	ds_read_b128 v[180:183], v147 offset:49152
	ds_read_b128 v[184:187], v147 offset:50176
	ds_read_b128 v[188:191], v147 offset:51200
	ds_read_b128 v[192:195], v147 offset:52224
	ds_read_b128 v[196:199], v147 offset:53248
	ds_read_b128 v[200:203], v147 offset:54272
	ds_read_b128 v[204:207], v147 offset:55296
	ds_read_b128 v[210:213], v147 offset:56320
	global_load_lds_dwordx4 v[214:215], off
	v_lshl_add_u64 v[214:215], v[216:217], 0, s[20:21]
	s_add_i32 m0, s40, 0x2000
	s_add_i32 s40, s79, s45
	global_load_lds_dwordx4 v[214:215], off
	v_lshl_add_u64 v[214:215], v[218:219], 0, s[20:21]
	s_mov_b32 m0, s40
	s_nop 0
	global_load_lds_dwordx4 v[214:215], off
	v_lshl_add_u64 v[214:215], v[220:221], 0, s[20:21]
	s_add_i32 m0, s40, 0x2000
	s_nop 0
	global_load_lds_dwordx4 v[214:215], off
	v_lshl_add_u64 v[214:215], v[222:223], 0, s[20:21]
	s_mov_b32 m0, s56
	s_nop 0
	global_load_lds_dwordx4 v[214:215], off
	v_lshl_add_u64 v[214:215], v[224:225], 0, s[20:21]
	s_mov_b32 m0, s57
	s_nop 0
	global_load_lds_dwordx4 v[214:215], off
	s_waitcnt vmcnt(8)
	s_waitcnt lgkmcnt(0)
	s_barrier
	s_setprio 1
	s_waitcnt lgkmcnt(0)
	v_mfma_f32_16x16x32_bf16 v[62:65], v[142:145], v[180:183], v[62:65]
	v_mfma_f32_16x16x32_bf16 v[58:61], v[156:159], v[180:183], v[58:61]
	v_mfma_f32_16x16x32_bf16 v[46:49], v[142:145], v[188:191], v[46:49]
	v_mfma_f32_16x16x32_bf16 v[42:45], v[156:159], v[188:191], v[42:45]
	v_mfma_f32_16x16x32_bf16 v[30:33], v[142:145], v[196:199], v[30:33]
	v_mfma_f32_16x16x32_bf16 v[26:29], v[156:159], v[196:199], v[26:29]
	v_mfma_f32_16x16x32_bf16 v[14:17], v[142:145], v[204:207], v[14:17]
	v_mfma_f32_16x16x32_bf16 v[10:13], v[156:159], v[204:207], v[10:13]
	v_mfma_f32_16x16x32_bf16 v[62:65], v[152:155], v[184:187], v[62:65]
	v_mfma_f32_16x16x32_bf16 v[58:61], v[160:163], v[184:187], v[58:61]
	v_mfma_f32_16x16x32_bf16 v[46:49], v[152:155], v[192:195], v[46:49]
	v_mfma_f32_16x16x32_bf16 v[42:45], v[160:163], v[192:195], v[42:45]
	v_mfma_f32_16x16x32_bf16 v[30:33], v[152:155], v[200:203], v[30:33]
	v_mfma_f32_16x16x32_bf16 v[26:29], v[160:163], v[200:203], v[26:29]
	v_mfma_f32_16x16x32_bf16 v[14:17], v[152:155], v[210:213], v[14:17]
	v_mfma_f32_16x16x32_bf16 v[10:13], v[160:163], v[210:213], v[10:13]
	s_setprio 0
	s_setprio 1
	v_mfma_f32_16x16x32_bf16 v[54:57], v[164:167], v[180:183], v[54:57]
	v_mfma_f32_16x16x32_bf16 v[50:53], v[172:175], v[180:183], v[50:53]
	v_mfma_f32_16x16x32_bf16 v[38:41], v[164:167], v[188:191], v[38:41]
	v_mfma_f32_16x16x32_bf16 v[34:37], v[172:175], v[188:191], v[34:37]
	v_mfma_f32_16x16x32_bf16 v[22:25], v[164:167], v[196:199], v[22:25]
	v_mfma_f32_16x16x32_bf16 v[18:21], v[172:175], v[196:199], v[18:21]
	v_mfma_f32_16x16x32_bf16 v[6:9], v[164:167], v[204:207], v[6:9]
	v_mfma_f32_16x16x32_bf16 v[2:5], v[172:175], v[204:207], v[2:5]
	v_mfma_f32_16x16x32_bf16 v[54:57], v[168:171], v[184:187], v[54:57]
	v_mfma_f32_16x16x32_bf16 v[50:53], v[176:179], v[184:187], v[50:53]
	v_mfma_f32_16x16x32_bf16 v[38:41], v[168:171], v[192:195], v[38:41]
	v_mfma_f32_16x16x32_bf16 v[34:37], v[176:179], v[192:195], v[34:37]
	v_mfma_f32_16x16x32_bf16 v[22:25], v[168:171], v[200:203], v[22:25]
	v_mfma_f32_16x16x32_bf16 v[18:21], v[176:179], v[200:203], v[18:21]
	v_mfma_f32_16x16x32_bf16 v[6:9], v[168:171], v[210:213], v[6:9]
	v_mfma_f32_16x16x32_bf16 v[2:5], v[176:179], v[210:213], v[2:5]
	s_setprio 2
	s_barrier
	s_add_u32 s77, s77, 0x100
	s_addc_u32 s78, s78, 0
	s_add_u32 s4, s4, 0x100
	s_addc_u32 s5, s5, 0
	s_cmp_ge_i32 s42, s55
	s_mov_b32 s40, s42
	s_cbranch_scc0 .LBB0_1087

.LBB0_1199:
	ds_read_b128 v[144:147], v153
	ds_read_b128 v[158:161], v153 offset:1024
	ds_read_b128 v[162:165], v153 offset:2048
	ds_read_b128 v[166:169], v153 offset:3072
	ds_read_b128 v[170:173], v154
	ds_read_b128 v[174:177], v154 offset:1024
	ds_read_b128 v[178:181], v154 offset:2048
	ds_read_b128 v[182:185], v154 offset:3072
	s_add_i32 s74, s38, 2
	s_add_u32 s75, s36, 0x80
	s_addc_u32 s39, s37, 0
	s_cmp_eq_u32 s61, s38
	s_cselect_b32 s38, s4, s75
	s_cselect_b32 s39, s5, s39
	s_cselect_b32 s77, s25, s73
	s_cselect_b32 s76, s24, s72
	v_lshl_add_u64 v[148:149], s[36:37], 0, v[140:141]
	s_add_i32 m0, s51, 0xc000
	ds_read_b128 v[186:189], v155
	ds_read_b128 v[190:193], v155 offset:1024
	ds_read_b128 v[194:197], v155 offset:2048
	ds_read_b128 v[198:201], v155 offset:3072
	ds_read_b128 v[202:205], v155 offset:4096
	ds_read_b128 v[210:213], v155 offset:5120
	ds_read_b128 v[214:217], v155 offset:6144
	ds_read_b128 v[218:221], v155 offset:7168
	global_load_lds_dwordx4 v[148:149], off
	v_lshl_add_u64 v[148:149], s[36:37], 0, v[138:139]
	s_add_i32 m0, s51, 0xe000
	s_nop 0
	global_load_lds_dwordx4 v[148:149], off
	s_waitcnt vmcnt(8)
	s_waitcnt lgkmcnt(0)
	s_barrier
	s_setprio 1
	s_waitcnt lgkmcnt(0)
	v_mfma_f32_16x16x32_bf16 v[122:125], v[144:147], v[186:189], v[122:125]
	v_mfma_f32_16x16x32_bf16 v[126:129], v[162:165], v[186:189], v[126:129]
	v_mfma_f32_16x16x32_bf16 v[110:113], v[144:147], v[194:197], v[110:113]
	v_mfma_f32_16x16x32_bf16 v[106:109], v[162:165], v[194:197], v[106:109]
	v_mfma_f32_16x16x32_bf16 v[94:97], v[144:147], v[202:205], v[94:97]
	v_mfma_f32_16x16x32_bf16 v[90:93], v[162:165], v[202:205], v[90:93]
	v_mfma_f32_16x16x32_bf16 v[78:81], v[144:147], v[214:217], v[78:81]
	v_mfma_f32_16x16x32_bf16 v[74:77], v[162:165], v[214:217], v[74:77]
	v_mfma_f32_16x16x32_bf16 v[122:125], v[158:161], v[190:193], v[122:125]
	v_mfma_f32_16x16x32_bf16 v[126:129], v[166:169], v[190:193], v[126:129]
	v_mfma_f32_16x16x32_bf16 v[110:113], v[158:161], v[198:201], v[110:113]
	v_mfma_f32_16x16x32_bf16 v[106:109], v[166:169], v[198:201], v[106:109]
	v_mfma_f32_16x16x32_bf16 v[94:97], v[158:161], v[210:213], v[94:97]
	v_mfma_f32_16x16x32_bf16 v[90:93], v[166:169], v[210:213], v[90:93]
	v_mfma_f32_16x16x32_bf16 v[78:81], v[158:161], v[218:221], v[78:81]
	v_mfma_f32_16x16x32_bf16 v[74:77], v[166:169], v[218:221], v[74:77]
	s_setprio 0
	s_setprio 1
	v_mfma_f32_16x16x32_bf16 v[118:121], v[170:173], v[186:189], v[118:121]
	v_mfma_f32_16x16x32_bf16 v[114:117], v[178:181], v[186:189], v[114:117]
	v_mfma_f32_16x16x32_bf16 v[102:105], v[170:173], v[194:197], v[102:105]
	v_mfma_f32_16x16x32_bf16 v[98:101], v[178:181], v[194:197], v[98:101]
	v_mfma_f32_16x16x32_bf16 v[86:89], v[170:173], v[202:205], v[86:89]
	v_mfma_f32_16x16x32_bf16 v[82:85], v[178:181], v[202:205], v[82:85]
	v_mfma_f32_16x16x32_bf16 v[70:73], v[170:173], v[214:217], v[70:73]
	v_mfma_f32_16x16x32_bf16 v[66:69], v[178:181], v[214:217], v[66:69]
	v_mfma_f32_16x16x32_bf16 v[118:121], v[174:177], v[190:193], v[118:121]
	v_mfma_f32_16x16x32_bf16 v[114:117], v[182:185], v[190:193], v[114:117]
	v_mfma_f32_16x16x32_bf16 v[102:105], v[174:177], v[198:201], v[102:105]
	v_mfma_f32_16x16x32_bf16 v[98:101], v[182:185], v[198:201], v[98:101]
	v_mfma_f32_16x16x32_bf16 v[86:89], v[174:177], v[210:213], v[86:89]
	v_mfma_f32_16x16x32_bf16 v[82:85], v[182:185], v[210:213], v[82:85]
	v_mfma_f32_16x16x32_bf16 v[70:73], v[174:177], v[218:221], v[70:73]
	v_mfma_f32_16x16x32_bf16 v[66:69], v[182:185], v[218:221], v[66:69]
	s_setprio 2
	s_barrier
	s_add_i32 s75, s63, s48
	v_lshl_add_u64 v[148:149], s[76:77], 0, v[130:131]
	s_mov_b32 m0, s75
	ds_read_b128 v[186:189], v155 offset:16384
	ds_read_b128 v[190:193], v155 offset:17408
	ds_read_b128 v[194:197], v155 offset:18432
	ds_read_b128 v[198:201], v155 offset:19456
	ds_read_b128 v[202:205], v155 offset:20480
	ds_read_b128 v[210:213], v155 offset:21504
	ds_read_b128 v[214:217], v155 offset:22528
	ds_read_b128 v[218:221], v155 offset:23552
	global_load_lds_dwordx4 v[148:149], off
	s_add_i32 m0, s75, 0x2000
	v_lshl_add_u64 v[206:207], s[76:77], 0, v[132:133]
	s_add_u32 s76, s76, s10
	s_addc_u32 s77, s77, s11
	s_add_i32 s75, s64, s48
	global_load_lds_dwordx4 v[206:207], off
	v_lshl_add_u64 v[222:223], s[76:77], 0, v[130:131]
	s_mov_b32 m0, s75
	v_lshl_add_u64 v[224:225], s[76:77], 0, v[132:133]
	global_load_lds_dwordx4 v[222:223], off
	s_add_i32 m0, s75, 0x2000
	v_lshl_add_u64 v[226:227], s[38:39], 0, v[134:135]
	global_load_lds_dwordx4 v[224:225], off
	s_mov_b32 m0, s51
	v_lshl_add_u64 v[228:229], s[38:39], 0, v[136:137]
	global_load_lds_dwordx4 v[226:227], off
	s_mov_b32 m0, s52
	s_nop 0
	global_load_lds_dwordx4 v[228:229], off
	s_waitcnt vmcnt(8)
	s_waitcnt lgkmcnt(0)
	s_barrier
	s_setprio 1
	s_waitcnt lgkmcnt(0)
	v_mfma_f32_16x16x32_bf16 v[62:65], v[144:147], v[186:189], v[62:65]
	v_mfma_f32_16x16x32_bf16 v[58:61], v[162:165], v[186:189], v[58:61]
	v_mfma_f32_16x16x32_bf16 v[46:49], v[144:147], v[194:197], v[46:49]
	v_mfma_f32_16x16x32_bf16 v[42:45], v[162:165], v[194:197], v[42:45]
	v_mfma_f32_16x16x32_bf16 v[30:33], v[144:147], v[202:205], v[30:33]
	v_mfma_f32_16x16x32_bf16 v[26:29], v[162:165], v[202:205], v[26:29]
	v_mfma_f32_16x16x32_bf16 v[14:17], v[144:147], v[214:217], v[14:17]
	v_mfma_f32_16x16x32_bf16 v[10:13], v[162:165], v[214:217], v[10:13]
	v_mfma_f32_16x16x32_bf16 v[62:65], v[158:161], v[190:193], v[62:65]
	v_mfma_f32_16x16x32_bf16 v[58:61], v[166:169], v[190:193], v[58:61]
	v_mfma_f32_16x16x32_bf16 v[46:49], v[158:161], v[198:201], v[46:49]
	v_mfma_f32_16x16x32_bf16 v[42:45], v[166:169], v[198:201], v[42:45]
	v_mfma_f32_16x16x32_bf16 v[30:33], v[158:161], v[210:213], v[30:33]
	v_mfma_f32_16x16x32_bf16 v[26:29], v[166:169], v[210:213], v[26:29]
	v_mfma_f32_16x16x32_bf16 v[14:17], v[158:161], v[218:221], v[14:17]
	v_mfma_f32_16x16x32_bf16 v[10:13], v[166:169], v[218:221], v[10:13]
	s_setprio 0
	s_setprio 1
	v_mfma_f32_16x16x32_bf16 v[54:57], v[170:173], v[186:189], v[54:57]
	v_mfma_f32_16x16x32_bf16 v[50:53], v[178:181], v[186:189], v[50:53]
	v_mfma_f32_16x16x32_bf16 v[38:41], v[170:173], v[194:197], v[38:41]
	v_mfma_f32_16x16x32_bf16 v[34:37], v[178:181], v[194:197], v[34:37]
	v_mfma_f32_16x16x32_bf16 v[22:25], v[170:173], v[202:205], v[22:25]
	v_mfma_f32_16x16x32_bf16 v[18:21], v[178:181], v[202:205], v[18:21]
	v_mfma_f32_16x16x32_bf16 v[6:9], v[170:173], v[214:217], v[6:9]
	v_mfma_f32_16x16x32_bf16 v[2:5], v[178:181], v[214:217], v[2:5]
	v_mfma_f32_16x16x32_bf16 v[54:57], v[174:177], v[190:193], v[54:57]
	v_mfma_f32_16x16x32_bf16 v[50:53], v[182:185], v[190:193], v[50:53]
	v_mfma_f32_16x16x32_bf16 v[38:41], v[174:177], v[198:201], v[38:41]
	v_mfma_f32_16x16x32_bf16 v[34:37], v[182:185], v[198:201], v[34:37]
	v_mfma_f32_16x16x32_bf16 v[22:25], v[174:177], v[210:213], v[22:25]
	v_mfma_f32_16x16x32_bf16 v[18:21], v[182:185], v[210:213], v[18:21]
	v_mfma_f32_16x16x32_bf16 v[6:9], v[174:177], v[218:221], v[6:9]
	v_mfma_f32_16x16x32_bf16 v[2:5], v[182:185], v[218:221], v[2:5]
	s_setprio 2
	s_barrier
	s_add_i32 s75, 0, 0x18000
	v_add_u32_e32 v157, s75, v152
	s_add_i32 s76, 0, 0x1c000
	ds_read_b128 v[144:147], v157
	ds_read_b128 v[158:161], v157 offset:1024
	ds_read_b128 v[162:165], v157 offset:2048
	ds_read_b128 v[166:169], v157 offset:3072
	v_add_u32_e32 v157, s76, v152
	ds_read_b128 v[170:173], v157
	ds_read_b128 v[174:177], v157 offset:1024
	ds_read_b128 v[178:181], v157 offset:2048
	ds_read_b128 v[182:185], v157 offset:3072
	s_add_u32 s38, s38, s10
	s_addc_u32 s39, s39, s11
	s_mov_b32 m0, s53
	v_lshl_add_u64 v[230:231], s[38:39], 0, v[134:135]
	ds_read_b128 v[186:189], v155 offset:32768
	ds_read_b128 v[190:193], v155 offset:33792
	ds_read_b128 v[194:197], v155 offset:34816
	ds_read_b128 v[198:201], v155 offset:35840
	ds_read_b128 v[202:205], v155 offset:36864
	ds_read_b128 v[210:213], v155 offset:37888
	ds_read_b128 v[214:217], v155 offset:38912
	ds_read_b128 v[218:221], v155 offset:39936
	global_load_lds_dwordx4 v[230:231], off
	v_lshl_add_u64 v[230:231], s[38:39], 0, v[136:137]
	s_mov_b32 m0, s54
	s_nop 0
	global_load_lds_dwordx4 v[230:231], off
	s_waitcnt vmcnt(8)
	s_waitcnt lgkmcnt(0)
	s_barrier
	s_setprio 1
	s_waitcnt lgkmcnt(0)
	v_mfma_f32_16x16x32_bf16 v[122:125], v[144:147], v[186:189], v[122:125]
	v_mfma_f32_16x16x32_bf16 v[126:129], v[162:165], v[186:189], v[126:129]
	v_mfma_f32_16x16x32_bf16 v[110:113], v[144:147], v[194:197], v[110:113]
	v_mfma_f32_16x16x32_bf16 v[106:109], v[162:165], v[194:197], v[106:109]
	v_mfma_f32_16x16x32_bf16 v[94:97], v[144:147], v[202:205], v[94:97]
	v_mfma_f32_16x16x32_bf16 v[90:93], v[162:165], v[202:205], v[90:93]
	v_mfma_f32_16x16x32_bf16 v[78:81], v[144:147], v[214:217], v[78:81]
	v_mfma_f32_16x16x32_bf16 v[74:77], v[162:165], v[214:217], v[74:77]
	v_mfma_f32_16x16x32_bf16 v[122:125], v[158:161], v[190:193], v[122:125]
	v_mfma_f32_16x16x32_bf16 v[126:129], v[166:169], v[190:193], v[126:129]
	v_mfma_f32_16x16x32_bf16 v[110:113], v[158:161], v[198:201], v[110:113]
	v_mfma_f32_16x16x32_bf16 v[106:109], v[166:169], v[198:201], v[106:109]
	v_mfma_f32_16x16x32_bf16 v[94:97], v[158:161], v[210:213], v[94:97]
	v_mfma_f32_16x16x32_bf16 v[90:93], v[166:169], v[210:213], v[90:93]
	v_mfma_f32_16x16x32_bf16 v[78:81], v[158:161], v[218:221], v[78:81]
	v_mfma_f32_16x16x32_bf16 v[74:77], v[166:169], v[218:221], v[74:77]
	s_setprio 0
	s_setprio 1
	v_mfma_f32_16x16x32_bf16 v[118:121], v[170:173], v[186:189], v[118:121]
	v_mfma_f32_16x16x32_bf16 v[114:117], v[178:181], v[186:189], v[114:117]
	v_mfma_f32_16x16x32_bf16 v[102:105], v[170:173], v[194:197], v[102:105]
	v_mfma_f32_16x16x32_bf16 v[98:101], v[178:181], v[194:197], v[98:101]
	v_mfma_f32_16x16x32_bf16 v[86:89], v[170:173], v[202:205], v[86:89]
	v_mfma_f32_16x16x32_bf16 v[82:85], v[178:181], v[202:205], v[82:85]
	v_mfma_f32_16x16x32_bf16 v[70:73], v[170:173], v[214:217], v[70:73]
	v_mfma_f32_16x16x32_bf16 v[66:69], v[178:181], v[214:217], v[66:69]
	v_mfma_f32_16x16x32_bf16 v[118:121], v[174:177], v[190:193], v[118:121]
	v_mfma_f32_16x16x32_bf16 v[114:117], v[182:185], v[190:193], v[114:117]
	v_mfma_f32_16x16x32_bf16 v[102:105], v[174:177], v[198:201], v[102:105]
	v_mfma_f32_16x16x32_bf16 v[98:101], v[182:185], v[198:201], v[98:101]
	v_mfma_f32_16x16x32_bf16 v[86:89], v[174:177], v[210:213], v[86:89]
	v_mfma_f32_16x16x32_bf16 v[82:85], v[182:185], v[210:213], v[82:85]
	v_mfma_f32_16x16x32_bf16 v[70:73], v[174:177], v[218:221], v[70:73]
	v_mfma_f32_16x16x32_bf16 v[66:69], v[182:185], v[218:221], v[66:69]
	s_setprio 2
	s_barrier
	s_add_i32 s38, s75, s48
	v_lshl_add_u64 v[148:149], v[148:149], 0, s[18:19]
	s_mov_b32 m0, s38
	ds_read_b128 v[186:189], v155 offset:49152
	ds_read_b128 v[190:193], v155 offset:50176
	ds_read_b128 v[194:197], v155 offset:51200
	ds_read_b128 v[198:201], v155 offset:52224
	ds_read_b128 v[202:205], v155 offset:53248
	ds_read_b128 v[210:213], v155 offset:54272
	ds_read_b128 v[214:217], v155 offset:55296
	ds_read_b128 v[218:221], v155 offset:56320
	global_load_lds_dwordx4 v[148:149], off
	v_lshl_add_u64 v[148:149], v[206:207], 0, s[18:19]
	s_add_i32 m0, s38, 0x2000
	s_add_i32 s38, s76, s48
	global_load_lds_dwordx4 v[148:149], off
	v_lshl_add_u64 v[148:149], v[222:223], 0, s[18:19]
	s_mov_b32 m0, s38
	s_nop 0
	global_load_lds_dwordx4 v[148:149], off
	v_lshl_add_u64 v[148:149], v[224:225], 0, s[18:19]
	s_add_i32 m0, s38, 0x2000
	s_nop 0
	global_load_lds_dwordx4 v[148:149], off
	v_lshl_add_u64 v[148:149], v[226:227], 0, s[18:19]
	s_mov_b32 m0, s57
	s_nop 0
	global_load_lds_dwordx4 v[148:149], off
	v_lshl_add_u64 v[148:149], v[228:229], 0, s[18:19]
	s_mov_b32 m0, s58
	s_nop 0
	global_load_lds_dwordx4 v[148:149], off
	s_waitcnt vmcnt(8)
	s_waitcnt lgkmcnt(0)
	s_barrier
	s_setprio 1
	s_waitcnt lgkmcnt(0)
	v_mfma_f32_16x16x32_bf16 v[62:65], v[144:147], v[186:189], v[62:65]
	v_mfma_f32_16x16x32_bf16 v[58:61], v[162:165], v[186:189], v[58:61]
	v_mfma_f32_16x16x32_bf16 v[46:49], v[144:147], v[194:197], v[46:49]
	v_mfma_f32_16x16x32_bf16 v[42:45], v[162:165], v[194:197], v[42:45]
	v_mfma_f32_16x16x32_bf16 v[30:33], v[144:147], v[202:205], v[30:33]
	v_mfma_f32_16x16x32_bf16 v[26:29], v[162:165], v[202:205], v[26:29]
	v_mfma_f32_16x16x32_bf16 v[14:17], v[144:147], v[214:217], v[14:17]
	v_mfma_f32_16x16x32_bf16 v[10:13], v[162:165], v[214:217], v[10:13]
	v_mfma_f32_16x16x32_bf16 v[62:65], v[158:161], v[190:193], v[62:65]
	v_mfma_f32_16x16x32_bf16 v[58:61], v[166:169], v[190:193], v[58:61]
	v_mfma_f32_16x16x32_bf16 v[46:49], v[158:161], v[198:201], v[46:49]
	v_mfma_f32_16x16x32_bf16 v[42:45], v[166:169], v[198:201], v[42:45]
	v_mfma_f32_16x16x32_bf16 v[30:33], v[158:161], v[210:213], v[30:33]
	v_mfma_f32_16x16x32_bf16 v[26:29], v[166:169], v[210:213], v[26:29]
	v_mfma_f32_16x16x32_bf16 v[14:17], v[158:161], v[218:221], v[14:17]
	v_mfma_f32_16x16x32_bf16 v[10:13], v[166:169], v[218:221], v[10:13]
	s_setprio 0
	s_setprio 1
	v_mfma_f32_16x16x32_bf16 v[54:57], v[170:173], v[186:189], v[54:57]
	v_mfma_f32_16x16x32_bf16 v[50:53], v[178:181], v[186:189], v[50:53]
	v_mfma_f32_16x16x32_bf16 v[38:41], v[170:173], v[194:197], v[38:41]
	v_mfma_f32_16x16x32_bf16 v[34:37], v[178:181], v[194:197], v[34:37]
	v_mfma_f32_16x16x32_bf16 v[22:25], v[170:173], v[202:205], v[22:25]
	v_mfma_f32_16x16x32_bf16 v[18:21], v[178:181], v[202:205], v[18:21]
	v_mfma_f32_16x16x32_bf16 v[6:9], v[170:173], v[214:217], v[6:9]
	v_mfma_f32_16x16x32_bf16 v[2:5], v[178:181], v[214:217], v[2:5]
	v_mfma_f32_16x16x32_bf16 v[54:57], v[174:177], v[190:193], v[54:57]
	v_mfma_f32_16x16x32_bf16 v[50:53], v[182:185], v[190:193], v[50:53]
	v_mfma_f32_16x16x32_bf16 v[38:41], v[174:177], v[198:201], v[38:41]
	v_mfma_f32_16x16x32_bf16 v[34:37], v[182:185], v[198:201], v[34:37]
	v_mfma_f32_16x16x32_bf16 v[22:25], v[174:177], v[210:213], v[22:25]
	v_mfma_f32_16x16x32_bf16 v[18:21], v[182:185], v[210:213], v[18:21]
	v_mfma_f32_16x16x32_bf16 v[6:9], v[174:177], v[218:221], v[6:9]
	v_mfma_f32_16x16x32_bf16 v[2:5], v[182:185], v[218:221], v[2:5]
	s_setprio 2
	s_barrier
	s_add_u32 s72, s72, 0x100
	s_addc_u32 s73, s73, 0
	s_add_u32 s36, s36, 0x100
	s_addc_u32 s37, s37, 0
	s_cmp_ge_i32 s74, s56
	s_mov_b32 s38, s74
	s_cbranch_scc0 .LBB0_1199

.LBB0_1297:
	v_add_u32_e32 v149, s67, v146
	ds_read_b128 v[142:145], v149
	ds_read_b128 v[152:155], v149 offset:1024
	ds_read_b128 v[156:159], v149 offset:2048
	ds_read_b128 v[160:163], v149 offset:3072
	v_add_u32_e32 v149, s70, v146
	ds_read_b128 v[164:167], v149
	ds_read_b128 v[168:171], v149 offset:1024
	ds_read_b128 v[172:175], v149 offset:2048
	ds_read_b128 v[176:179], v149 offset:3072
	s_add_i32 s42, s40, 2
	s_add_u32 s43, s4, 0x80
	s_addc_u32 s41, s5, 0
	s_cmp_eq_u32 s56, s40
	s_cselect_b32 s40, s36, s43
	s_cselect_b32 s41, s37, s41
	s_cselect_b32 s79, s39, s76
	s_cselect_b32 s78, s38, s75
	v_lshl_add_u64 v[214:215], s[4:5], 0, v[140:141]
	s_add_i32 m0, s48, 0xc000
	ds_read_b128 v[180:183], v147
	ds_read_b128 v[184:187], v147 offset:1024
	ds_read_b128 v[188:191], v147 offset:2048
	ds_read_b128 v[192:195], v147 offset:3072
	ds_read_b128 v[196:199], v147 offset:4096
	ds_read_b128 v[200:203], v147 offset:5120
	ds_read_b128 v[204:207], v147 offset:6144
	ds_read_b128 v[210:213], v147 offset:7168
	global_load_lds_dwordx4 v[214:215], off
	v_lshl_add_u64 v[214:215], s[4:5], 0, v[138:139]
	s_add_i32 m0, s48, 0xe000
	s_nop 0
	global_load_lds_dwordx4 v[214:215], off
	s_waitcnt vmcnt(8)
	s_waitcnt lgkmcnt(0)
	s_barrier
	s_setprio 1
	s_waitcnt lgkmcnt(0)
	v_mfma_f32_16x16x32_bf16 v[118:121], v[142:145], v[180:183], v[118:121]
	v_mfma_f32_16x16x32_bf16 v[122:125], v[156:159], v[180:183], v[122:125]
	v_mfma_f32_16x16x32_bf16 v[94:97], v[142:145], v[188:191], v[94:97]
	v_mfma_f32_16x16x32_bf16 v[106:109], v[156:159], v[188:191], v[106:109]
	v_mfma_f32_16x16x32_bf16 v[78:81], v[142:145], v[196:199], v[78:81]
	v_mfma_f32_16x16x32_bf16 v[90:93], v[156:159], v[196:199], v[90:93]
	v_mfma_f32_16x16x32_bf16 v[54:57], v[142:145], v[204:207], v[54:57]
	v_mfma_f32_16x16x32_bf16 v[74:77], v[156:159], v[204:207], v[74:77]
	v_mfma_f32_16x16x32_bf16 v[118:121], v[152:155], v[184:187], v[118:121]
	v_mfma_f32_16x16x32_bf16 v[122:125], v[160:163], v[184:187], v[122:125]
	v_mfma_f32_16x16x32_bf16 v[94:97], v[152:155], v[192:195], v[94:97]
	v_mfma_f32_16x16x32_bf16 v[106:109], v[160:163], v[192:195], v[106:109]
	v_mfma_f32_16x16x32_bf16 v[78:81], v[152:155], v[200:203], v[78:81]
	v_mfma_f32_16x16x32_bf16 v[90:93], v[160:163], v[200:203], v[90:93]
	v_mfma_f32_16x16x32_bf16 v[54:57], v[152:155], v[210:213], v[54:57]
	v_mfma_f32_16x16x32_bf16 v[74:77], v[160:163], v[210:213], v[74:77]
	s_setprio 0
	s_setprio 1
	v_mfma_f32_16x16x32_bf16 v[114:117], v[164:167], v[180:183], v[114:117]
	v_mfma_f32_16x16x32_bf16 v[126:129], v[172:175], v[180:183], v[126:129]
	v_mfma_f32_16x16x32_bf16 v[102:105], v[164:167], v[188:191], v[102:105]
	v_mfma_f32_16x16x32_bf16 v[110:113], v[172:175], v[188:191], v[110:113]
	v_mfma_f32_16x16x32_bf16 v[86:89], v[164:167], v[196:199], v[86:89]
	v_mfma_f32_16x16x32_bf16 v[98:101], v[172:175], v[196:199], v[98:101]
	v_mfma_f32_16x16x32_bf16 v[70:73], v[164:167], v[204:207], v[70:73]
	v_mfma_f32_16x16x32_bf16 v[82:85], v[172:175], v[204:207], v[82:85]
	v_mfma_f32_16x16x32_bf16 v[114:117], v[168:171], v[184:187], v[114:117]
	v_mfma_f32_16x16x32_bf16 v[126:129], v[176:179], v[184:187], v[126:129]
	v_mfma_f32_16x16x32_bf16 v[102:105], v[168:171], v[192:195], v[102:105]
	v_mfma_f32_16x16x32_bf16 v[110:113], v[176:179], v[192:195], v[110:113]
	v_mfma_f32_16x16x32_bf16 v[86:89], v[168:171], v[200:203], v[86:89]
	v_mfma_f32_16x16x32_bf16 v[98:101], v[176:179], v[200:203], v[98:101]
	v_mfma_f32_16x16x32_bf16 v[70:73], v[168:171], v[210:213], v[70:73]
	v_mfma_f32_16x16x32_bf16 v[82:85], v[176:179], v[210:213], v[82:85]
	s_setprio 2
	s_barrier
	s_add_i32 s43, s67, s45
	v_lshl_add_u64 v[214:215], s[78:79], 0, v[130:131]
	s_mov_b32 m0, s43
	ds_read_b128 v[180:183], v147 offset:16384
	ds_read_b128 v[184:187], v147 offset:17408
	ds_read_b128 v[188:191], v147 offset:18432
	ds_read_b128 v[192:195], v147 offset:19456
	ds_read_b128 v[196:199], v147 offset:20480
	ds_read_b128 v[200:203], v147 offset:21504
	ds_read_b128 v[204:207], v147 offset:22528
	ds_read_b128 v[210:213], v147 offset:23552
	global_load_lds_dwordx4 v[214:215], off
	s_add_i32 m0, s43, 0x2000
	v_lshl_add_u64 v[216:217], s[78:79], 0, v[132:133]
	s_add_u32 s78, s78, s14
	s_addc_u32 s79, s79, s15
	s_add_i32 s43, s70, s45
	global_load_lds_dwordx4 v[216:217], off
	v_lshl_add_u64 v[218:219], s[78:79], 0, v[130:131]
	s_mov_b32 m0, s43
	v_lshl_add_u64 v[220:221], s[78:79], 0, v[132:133]
	global_load_lds_dwordx4 v[218:219], off
	s_add_i32 m0, s43, 0x2000
	v_lshl_add_u64 v[222:223], s[40:41], 0, v[134:135]
	global_load_lds_dwordx4 v[220:221], off
	s_mov_b32 m0, s48
	v_lshl_add_u64 v[224:225], s[40:41], 0, v[136:137]
	global_load_lds_dwordx4 v[222:223], off
	s_mov_b32 m0, s49
	s_nop 0
	global_load_lds_dwordx4 v[224:225], off
	s_waitcnt vmcnt(8)
	s_waitcnt lgkmcnt(0)
	s_barrier
	s_setprio 1
	s_waitcnt lgkmcnt(0)
	v_mfma_f32_16x16x32_bf16 v[30:33], v[142:145], v[180:183], v[30:33]
	v_mfma_f32_16x16x32_bf16 v[42:45], v[156:159], v[180:183], v[42:45]
	v_mfma_f32_16x16x32_bf16 v[14:17], v[142:145], v[188:191], v[14:17]
	v_mfma_f32_16x16x32_bf16 v[26:29], v[156:159], v[188:191], v[26:29]
	v_mfma_f32_16x16x32_bf16 v[2:5], v[142:145], v[196:199], v[2:5]
	v_mfma_f32_16x16x32_bf16 v[10:13], v[156:159], v[196:199], v[10:13]
	v_mfma_f32_16x16x32_bf16 v[50:53], v[142:145], v[204:207], v[50:53]
	v_mfma_f32_16x16x32_bf16 v[58:61], v[156:159], v[204:207], v[58:61]
	v_mfma_f32_16x16x32_bf16 v[30:33], v[152:155], v[184:187], v[30:33]
	v_mfma_f32_16x16x32_bf16 v[42:45], v[160:163], v[184:187], v[42:45]
	v_mfma_f32_16x16x32_bf16 v[14:17], v[152:155], v[192:195], v[14:17]
	v_mfma_f32_16x16x32_bf16 v[26:29], v[160:163], v[192:195], v[26:29]
	v_mfma_f32_16x16x32_bf16 v[2:5], v[152:155], v[200:203], v[2:5]
	v_mfma_f32_16x16x32_bf16 v[10:13], v[160:163], v[200:203], v[10:13]
	v_mfma_f32_16x16x32_bf16 v[50:53], v[152:155], v[210:213], v[50:53]
	v_mfma_f32_16x16x32_bf16 v[58:61], v[160:163], v[210:213], v[58:61]
	s_setprio 0
	s_setprio 1
	v_mfma_f32_16x16x32_bf16 v[38:41], v[164:167], v[180:183], v[38:41]
	v_mfma_f32_16x16x32_bf16 v[62:65], v[172:175], v[180:183], v[62:65]
	v_mfma_f32_16x16x32_bf16 v[22:25], v[164:167], v[188:191], v[22:25]
	v_mfma_f32_16x16x32_bf16 v[34:37], v[172:175], v[188:191], v[34:37]
	v_mfma_f32_16x16x32_bf16 v[6:9], v[164:167], v[196:199], v[6:9]
	v_mfma_f32_16x16x32_bf16 v[18:21], v[172:175], v[196:199], v[18:21]
	v_mfma_f32_16x16x32_bf16 v[46:49], v[164:167], v[204:207], v[46:49]
	v_mfma_f32_16x16x32_bf16 v[66:69], v[172:175], v[204:207], v[66:69]
	v_mfma_f32_16x16x32_bf16 v[38:41], v[168:171], v[184:187], v[38:41]
	v_mfma_f32_16x16x32_bf16 v[62:65], v[176:179], v[184:187], v[62:65]
	v_mfma_f32_16x16x32_bf16 v[22:25], v[168:171], v[192:195], v[22:25]
	v_mfma_f32_16x16x32_bf16 v[34:37], v[176:179], v[192:195], v[34:37]
	v_mfma_f32_16x16x32_bf16 v[6:9], v[168:171], v[200:203], v[6:9]
	v_mfma_f32_16x16x32_bf16 v[18:21], v[176:179], v[200:203], v[18:21]
	v_mfma_f32_16x16x32_bf16 v[46:49], v[168:171], v[210:213], v[46:49]
	v_mfma_f32_16x16x32_bf16 v[66:69], v[176:179], v[210:213], v[66:69]
	s_setprio 2
	s_barrier
	s_add_i32 s43, 0, 0x18000
	v_add_u32_e32 v149, s43, v146
	s_add_i32 s77, 0, 0x1c000
	ds_read_b128 v[142:145], v149
	ds_read_b128 v[152:155], v149 offset:1024
	ds_read_b128 v[156:159], v149 offset:2048
	ds_read_b128 v[160:163], v149 offset:3072
	v_add_u32_e32 v149, s77, v146
	ds_read_b128 v[164:167], v149
	ds_read_b128 v[168:171], v149 offset:1024
	ds_read_b128 v[172:175], v149 offset:2048
	ds_read_b128 v[176:179], v149 offset:3072
	s_add_u32 s40, s40, s14
	s_addc_u32 s41, s41, s15
	s_mov_b32 m0, s50
	v_lshl_add_u64 v[226:227], s[40:41], 0, v[134:135]
	ds_read_b128 v[180:183], v147 offset:32768
	ds_read_b128 v[184:187], v147 offset:33792
	ds_read_b128 v[188:191], v147 offset:34816
	ds_read_b128 v[192:195], v147 offset:35840
	ds_read_b128 v[196:199], v147 offset:36864
	ds_read_b128 v[200:203], v147 offset:37888
	ds_read_b128 v[204:207], v147 offset:38912
	ds_read_b128 v[210:213], v147 offset:39936
	global_load_lds_dwordx4 v[226:227], off
	v_lshl_add_u64 v[226:227], s[40:41], 0, v[136:137]
	s_mov_b32 m0, s51
	s_nop 0
	global_load_lds_dwordx4 v[226:227], off
	s_waitcnt vmcnt(8)
	s_waitcnt lgkmcnt(0)
	s_barrier
	s_setprio 1
	s_waitcnt lgkmcnt(0)
	v_mfma_f32_16x16x32_bf16 v[118:121], v[142:145], v[180:183], v[118:121]
	v_mfma_f32_16x16x32_bf16 v[122:125], v[156:159], v[180:183], v[122:125]
	v_mfma_f32_16x16x32_bf16 v[94:97], v[142:145], v[188:191], v[94:97]
	v_mfma_f32_16x16x32_bf16 v[106:109], v[156:159], v[188:191], v[106:109]
	v_mfma_f32_16x16x32_bf16 v[78:81], v[142:145], v[196:199], v[78:81]
	v_mfma_f32_16x16x32_bf16 v[90:93], v[156:159], v[196:199], v[90:93]
	v_mfma_f32_16x16x32_bf16 v[54:57], v[142:145], v[204:207], v[54:57]
	v_mfma_f32_16x16x32_bf16 v[74:77], v[156:159], v[204:207], v[74:77]
	v_mfma_f32_16x16x32_bf16 v[118:121], v[152:155], v[184:187], v[118:121]
	v_mfma_f32_16x16x32_bf16 v[122:125], v[160:163], v[184:187], v[122:125]
	v_mfma_f32_16x16x32_bf16 v[94:97], v[152:155], v[192:195], v[94:97]
	v_mfma_f32_16x16x32_bf16 v[106:109], v[160:163], v[192:195], v[106:109]
	v_mfma_f32_16x16x32_bf16 v[78:81], v[152:155], v[200:203], v[78:81]
	v_mfma_f32_16x16x32_bf16 v[90:93], v[160:163], v[200:203], v[90:93]
	v_mfma_f32_16x16x32_bf16 v[54:57], v[152:155], v[210:213], v[54:57]
	v_mfma_f32_16x16x32_bf16 v[74:77], v[160:163], v[210:213], v[74:77]
	s_setprio 0
	s_setprio 1
	v_mfma_f32_16x16x32_bf16 v[114:117], v[164:167], v[180:183], v[114:117]
	v_mfma_f32_16x16x32_bf16 v[126:129], v[172:175], v[180:183], v[126:129]
	v_mfma_f32_16x16x32_bf16 v[102:105], v[164:167], v[188:191], v[102:105]
	v_mfma_f32_16x16x32_bf16 v[110:113], v[172:175], v[188:191], v[110:113]
	v_mfma_f32_16x16x32_bf16 v[86:89], v[164:167], v[196:199], v[86:89]
	v_mfma_f32_16x16x32_bf16 v[98:101], v[172:175], v[196:199], v[98:101]
	v_mfma_f32_16x16x32_bf16 v[70:73], v[164:167], v[204:207], v[70:73]
	v_mfma_f32_16x16x32_bf16 v[82:85], v[172:175], v[204:207], v[82:85]
	v_mfma_f32_16x16x32_bf16 v[114:117], v[168:171], v[184:187], v[114:117]
	v_mfma_f32_16x16x32_bf16 v[126:129], v[176:179], v[184:187], v[126:129]
	v_mfma_f32_16x16x32_bf16 v[102:105], v[168:171], v[192:195], v[102:105]
	v_mfma_f32_16x16x32_bf16 v[110:113], v[176:179], v[192:195], v[110:113]
	v_mfma_f32_16x16x32_bf16 v[86:89], v[168:171], v[200:203], v[86:89]
	v_mfma_f32_16x16x32_bf16 v[98:101], v[176:179], v[200:203], v[98:101]
	v_mfma_f32_16x16x32_bf16 v[70:73], v[168:171], v[210:213], v[70:73]
	v_mfma_f32_16x16x32_bf16 v[82:85], v[176:179], v[210:213], v[82:85]
	s_setprio 2
	s_barrier
	s_add_i32 s40, s43, s45
	v_lshl_add_u64 v[214:215], v[214:215], 0, s[20:21]
	s_mov_b32 m0, s40
	ds_read_b128 v[180:183], v147 offset:49152
	ds_read_b128 v[184:187], v147 offset:50176
	ds_read_b128 v[188:191], v147 offset:51200
	ds_read_b128 v[192:195], v147 offset:52224
	ds_read_b128 v[196:199], v147 offset:53248
	ds_read_b128 v[200:203], v147 offset:54272
	ds_read_b128 v[204:207], v147 offset:55296
	ds_read_b128 v[210:213], v147 offset:56320
	global_load_lds_dwordx4 v[214:215], off
	v_lshl_add_u64 v[214:215], v[216:217], 0, s[20:21]
	s_add_i32 m0, s40, 0x2000
	s_add_i32 s40, s77, s45
	global_load_lds_dwordx4 v[214:215], off
	v_lshl_add_u64 v[214:215], v[218:219], 0, s[20:21]
	s_mov_b32 m0, s40
	s_nop 0
	global_load_lds_dwordx4 v[214:215], off
	v_lshl_add_u64 v[214:215], v[220:221], 0, s[20:21]
	s_add_i32 m0, s40, 0x2000
	s_nop 0
	global_load_lds_dwordx4 v[214:215], off
	v_lshl_add_u64 v[214:215], v[222:223], 0, s[20:21]
	s_mov_b32 m0, s54
	s_nop 0
	global_load_lds_dwordx4 v[214:215], off
	v_lshl_add_u64 v[214:215], v[224:225], 0, s[20:21]
	s_mov_b32 m0, s55
	s_nop 0
	global_load_lds_dwordx4 v[214:215], off
	s_waitcnt vmcnt(8)
	s_waitcnt lgkmcnt(0)
	s_barrier
	s_setprio 1
	s_waitcnt lgkmcnt(0)
	v_mfma_f32_16x16x32_bf16 v[30:33], v[142:145], v[180:183], v[30:33]
	v_mfma_f32_16x16x32_bf16 v[42:45], v[156:159], v[180:183], v[42:45]
	v_mfma_f32_16x16x32_bf16 v[14:17], v[142:145], v[188:191], v[14:17]
	v_mfma_f32_16x16x32_bf16 v[26:29], v[156:159], v[188:191], v[26:29]
	v_mfma_f32_16x16x32_bf16 v[2:5], v[142:145], v[196:199], v[2:5]
	v_mfma_f32_16x16x32_bf16 v[10:13], v[156:159], v[196:199], v[10:13]
	v_mfma_f32_16x16x32_bf16 v[50:53], v[142:145], v[204:207], v[50:53]
	v_mfma_f32_16x16x32_bf16 v[58:61], v[156:159], v[204:207], v[58:61]
	v_mfma_f32_16x16x32_bf16 v[30:33], v[152:155], v[184:187], v[30:33]
	v_mfma_f32_16x16x32_bf16 v[42:45], v[160:163], v[184:187], v[42:45]
	v_mfma_f32_16x16x32_bf16 v[14:17], v[152:155], v[192:195], v[14:17]
	v_mfma_f32_16x16x32_bf16 v[26:29], v[160:163], v[192:195], v[26:29]
	v_mfma_f32_16x16x32_bf16 v[2:5], v[152:155], v[200:203], v[2:5]
	v_mfma_f32_16x16x32_bf16 v[10:13], v[160:163], v[200:203], v[10:13]
	v_mfma_f32_16x16x32_bf16 v[50:53], v[152:155], v[210:213], v[50:53]
	v_mfma_f32_16x16x32_bf16 v[58:61], v[160:163], v[210:213], v[58:61]
	s_setprio 0
	s_setprio 1
	v_mfma_f32_16x16x32_bf16 v[38:41], v[164:167], v[180:183], v[38:41]
	v_mfma_f32_16x16x32_bf16 v[62:65], v[172:175], v[180:183], v[62:65]
	v_mfma_f32_16x16x32_bf16 v[22:25], v[164:167], v[188:191], v[22:25]
	v_mfma_f32_16x16x32_bf16 v[34:37], v[172:175], v[188:191], v[34:37]
	v_mfma_f32_16x16x32_bf16 v[6:9], v[164:167], v[196:199], v[6:9]
	v_mfma_f32_16x16x32_bf16 v[18:21], v[172:175], v[196:199], v[18:21]
	v_mfma_f32_16x16x32_bf16 v[46:49], v[164:167], v[204:207], v[46:49]
	v_mfma_f32_16x16x32_bf16 v[66:69], v[172:175], v[204:207], v[66:69]
	v_mfma_f32_16x16x32_bf16 v[38:41], v[168:171], v[184:187], v[38:41]
	v_mfma_f32_16x16x32_bf16 v[62:65], v[176:179], v[184:187], v[62:65]
	v_mfma_f32_16x16x32_bf16 v[22:25], v[168:171], v[192:195], v[22:25]
	v_mfma_f32_16x16x32_bf16 v[34:37], v[176:179], v[192:195], v[34:37]
	v_mfma_f32_16x16x32_bf16 v[6:9], v[168:171], v[200:203], v[6:9]
	v_mfma_f32_16x16x32_bf16 v[18:21], v[176:179], v[200:203], v[18:21]
	v_mfma_f32_16x16x32_bf16 v[46:49], v[168:171], v[210:213], v[46:49]
	v_mfma_f32_16x16x32_bf16 v[66:69], v[176:179], v[210:213], v[66:69]
	s_setprio 2
	s_barrier
	s_add_u32 s75, s75, 0x100
	s_addc_u32 s76, s76, 0
	s_add_u32 s4, s4, 0x100
	s_addc_u32 s5, s5, 0
	s_cmp_ge_i32 s42, s53
	s_mov_b32 s40, s42
	s_cbranch_scc0 .LBB0_1297

.LBB0_1446:
	s_add_i32 s36, s44, 2
	ds_read_b128 v[140:143], v192
	ds_read_b128 v[144:147], v192 offset:1024
	ds_read_b128 v[148:151], v192 offset:2048
	ds_read_b128 v[152:155], v192 offset:3072
	ds_read_b128 v[156:159], v193
	ds_read_b128 v[160:163], v193 offset:1024
	ds_read_b128 v[164:167], v193 offset:2048
	ds_read_b128 v[168:171], v193 offset:3072
	s_or_b32 s72, s44, 1
	s_lshl_b64 s[74:75], s[36:37], 7
	s_add_u32 s71, s0, s74
	s_addc_u32 s45, s1, s75
	s_cmp_eq_u32 s44, s55
	s_cselect_b32 s74, 0, s74
	s_mov_b32 s73, s37
	s_cselect_b32 s45, s43, s45
	s_cselect_b32 s44, s42, s71
	s_cselect_b32 s71, 0, s75
	s_add_u32 s74, s22, s74
	s_addc_u32 s75, s23, s71
	s_lshl_b64 s[72:73], s[72:73], 7
	s_add_u32 s72, s69, s72
	s_addc_u32 s73, s70, s73
	s_mov_b32 m0, s56
	v_lshl_add_u64 v[188:189], s[72:73], 0, v[134:135]
	ds_read_b128 v[172:175], v194
	ds_read_b128 v[176:179], v194 offset:1024
	ds_read_b128 v[180:183], v194 offset:2048
	ds_read_b128 v[184:187], v194 offset:3072
	ds_read_b128 v[200:203], v194 offset:4096
	ds_read_b128 v[204:207], v194 offset:5120
	ds_read_b128 v[210:213], v194 offset:6144
	ds_read_b128 v[214:217], v194 offset:7168
	global_load_lds_dwordx4 v[188:189], off
	v_lshl_add_u64 v[188:189], s[72:73], 0, v[136:137]
	s_mov_b32 m0, s57
	s_nop 0
	global_load_lds_dwordx4 v[188:189], off
	s_waitcnt vmcnt(8)
	s_waitcnt lgkmcnt(0)
	s_barrier
	s_setprio 1
	s_waitcnt lgkmcnt(0)
	v_mfma_f32_16x16x32_bf16 v[126:129], v[140:143], v[172:175], v[126:129]
	v_mfma_f32_16x16x32_bf16 v[122:125], v[148:151], v[172:175], v[122:125]
	v_mfma_f32_16x16x32_bf16 v[110:113], v[140:143], v[180:183], v[110:113]
	v_mfma_f32_16x16x32_bf16 v[106:109], v[148:151], v[180:183], v[106:109]
	v_mfma_f32_16x16x32_bf16 v[94:97], v[140:143], v[200:203], v[94:97]
	v_mfma_f32_16x16x32_bf16 v[90:93], v[148:151], v[200:203], v[90:93]
	v_mfma_f32_16x16x32_bf16 v[78:81], v[140:143], v[210:213], v[78:81]
	v_mfma_f32_16x16x32_bf16 v[74:77], v[148:151], v[210:213], v[74:77]
	v_mfma_f32_16x16x32_bf16 v[126:129], v[144:147], v[176:179], v[126:129]
	v_mfma_f32_16x16x32_bf16 v[122:125], v[152:155], v[176:179], v[122:125]
	v_mfma_f32_16x16x32_bf16 v[110:113], v[144:147], v[184:187], v[110:113]
	v_mfma_f32_16x16x32_bf16 v[106:109], v[152:155], v[184:187], v[106:109]
	v_mfma_f32_16x16x32_bf16 v[94:97], v[144:147], v[204:207], v[94:97]
	v_mfma_f32_16x16x32_bf16 v[90:93], v[152:155], v[204:207], v[90:93]
	v_mfma_f32_16x16x32_bf16 v[78:81], v[144:147], v[214:217], v[78:81]
	v_mfma_f32_16x16x32_bf16 v[74:77], v[152:155], v[214:217], v[74:77]
	s_setprio 0
	s_setprio 1
	v_mfma_f32_16x16x32_bf16 v[118:121], v[156:159], v[172:175], v[118:121]
	v_mfma_f32_16x16x32_bf16 v[114:117], v[164:167], v[172:175], v[114:117]
	v_mfma_f32_16x16x32_bf16 v[102:105], v[156:159], v[180:183], v[102:105]
	v_mfma_f32_16x16x32_bf16 v[98:101], v[164:167], v[180:183], v[98:101]
	v_mfma_f32_16x16x32_bf16 v[86:89], v[156:159], v[200:203], v[86:89]
	v_mfma_f32_16x16x32_bf16 v[82:85], v[164:167], v[200:203], v[82:85]
	v_mfma_f32_16x16x32_bf16 v[70:73], v[156:159], v[210:213], v[70:73]
	v_mfma_f32_16x16x32_bf16 v[66:69], v[164:167], v[210:213], v[66:69]
	v_mfma_f32_16x16x32_bf16 v[118:121], v[160:163], v[176:179], v[118:121]
	v_mfma_f32_16x16x32_bf16 v[114:117], v[168:171], v[176:179], v[114:117]
	v_mfma_f32_16x16x32_bf16 v[102:105], v[160:163], v[184:187], v[102:105]
	v_mfma_f32_16x16x32_bf16 v[98:101], v[168:171], v[184:187], v[98:101]
	v_mfma_f32_16x16x32_bf16 v[86:89], v[160:163], v[204:207], v[86:89]
	v_mfma_f32_16x16x32_bf16 v[82:85], v[168:171], v[204:207], v[82:85]
	v_mfma_f32_16x16x32_bf16 v[70:73], v[160:163], v[214:217], v[70:73]
	v_mfma_f32_16x16x32_bf16 v[66:69], v[168:171], v[214:217], v[66:69]
	s_setprio 2
	s_barrier
	s_mov_b32 m0, s58
	v_lshl_add_u64 v[188:189], s[74:75], 0, v[130:131]
	s_add_u32 s72, s74, s24
	ds_read_b128 v[172:175], v194 offset:16384
	ds_read_b128 v[176:179], v194 offset:17408
	ds_read_b128 v[180:183], v194 offset:18432
	ds_read_b128 v[184:187], v194 offset:19456
	ds_read_b128 v[200:203], v194 offset:20480
	ds_read_b128 v[204:207], v194 offset:21504
	ds_read_b128 v[210:213], v194 offset:22528
	ds_read_b128 v[214:217], v194 offset:23552
	global_load_lds_dwordx4 v[188:189], off
	v_lshl_add_u64 v[218:219], s[74:75], 0, v[132:133]
	s_mov_b32 m0, s59
	s_addc_u32 s73, s75, s25
	global_load_lds_dwordx4 v[218:219], off
	v_lshl_add_u64 v[220:221], s[72:73], 0, v[130:131]
	s_mov_b32 m0, s60
	v_lshl_add_u64 v[222:223], s[72:73], 0, v[132:133]
	global_load_lds_dwordx4 v[220:221], off
	s_mov_b32 m0, s61
	v_lshl_add_u64 v[224:225], s[44:45], 0, v[134:135]
	global_load_lds_dwordx4 v[222:223], off
	s_mov_b32 m0, s33
	v_lshl_add_u64 v[226:227], s[44:45], 0, v[136:137]
	global_load_lds_dwordx4 v[224:225], off
	s_mov_b32 m0, s35
	s_nop 0
	global_load_lds_dwordx4 v[226:227], off
	s_waitcnt vmcnt(8)
	s_waitcnt lgkmcnt(0)
	s_barrier
	s_setprio 1
	s_waitcnt lgkmcnt(0)
	v_mfma_f32_16x16x32_bf16 v[62:65], v[140:143], v[172:175], v[62:65]
	v_mfma_f32_16x16x32_bf16 v[58:61], v[148:151], v[172:175], v[58:61]
	v_mfma_f32_16x16x32_bf16 v[46:49], v[140:143], v[180:183], v[46:49]
	v_mfma_f32_16x16x32_bf16 v[42:45], v[148:151], v[180:183], v[42:45]
	v_mfma_f32_16x16x32_bf16 v[30:33], v[140:143], v[200:203], v[30:33]
	v_mfma_f32_16x16x32_bf16 v[26:29], v[148:151], v[200:203], v[26:29]
	v_mfma_f32_16x16x32_bf16 v[14:17], v[140:143], v[210:213], v[14:17]
	v_mfma_f32_16x16x32_bf16 v[10:13], v[148:151], v[210:213], v[10:13]
	v_mfma_f32_16x16x32_bf16 v[62:65], v[144:147], v[176:179], v[62:65]
	v_mfma_f32_16x16x32_bf16 v[58:61], v[152:155], v[176:179], v[58:61]
	v_mfma_f32_16x16x32_bf16 v[46:49], v[144:147], v[184:187], v[46:49]
	v_mfma_f32_16x16x32_bf16 v[42:45], v[152:155], v[184:187], v[42:45]
	v_mfma_f32_16x16x32_bf16 v[30:33], v[144:147], v[204:207], v[30:33]
	v_mfma_f32_16x16x32_bf16 v[26:29], v[152:155], v[204:207], v[26:29]
	v_mfma_f32_16x16x32_bf16 v[14:17], v[144:147], v[214:217], v[14:17]
	v_mfma_f32_16x16x32_bf16 v[10:13], v[152:155], v[214:217], v[10:13]
	s_setprio 0
	s_setprio 1
	v_mfma_f32_16x16x32_bf16 v[54:57], v[156:159], v[172:175], v[54:57]
	v_mfma_f32_16x16x32_bf16 v[50:53], v[164:167], v[172:175], v[50:53]
	v_mfma_f32_16x16x32_bf16 v[38:41], v[156:159], v[180:183], v[38:41]
	v_mfma_f32_16x16x32_bf16 v[34:37], v[164:167], v[180:183], v[34:37]
	v_mfma_f32_16x16x32_bf16 v[22:25], v[156:159], v[200:203], v[22:25]
	v_mfma_f32_16x16x32_bf16 v[18:21], v[164:167], v[200:203], v[18:21]
	v_mfma_f32_16x16x32_bf16 v[6:9], v[156:159], v[210:213], v[6:9]
	v_mfma_f32_16x16x32_bf16 v[2:5], v[164:167], v[210:213], v[2:5]
	v_mfma_f32_16x16x32_bf16 v[54:57], v[160:163], v[176:179], v[54:57]
	v_mfma_f32_16x16x32_bf16 v[50:53], v[168:171], v[176:179], v[50:53]
	v_mfma_f32_16x16x32_bf16 v[38:41], v[160:163], v[184:187], v[38:41]
	v_mfma_f32_16x16x32_bf16 v[34:37], v[168:171], v[184:187], v[34:37]
	v_mfma_f32_16x16x32_bf16 v[22:25], v[160:163], v[204:207], v[22:25]
	v_mfma_f32_16x16x32_bf16 v[18:21], v[168:171], v[204:207], v[18:21]
	v_mfma_f32_16x16x32_bf16 v[6:9], v[160:163], v[214:217], v[6:9]
	v_mfma_f32_16x16x32_bf16 v[2:5], v[168:171], v[214:217], v[2:5]
	s_setprio 2
	s_barrier
	ds_read_b128 v[140:143], v195
	ds_read_b128 v[144:147], v195 offset:1024
	ds_read_b128 v[148:151], v195 offset:2048
	ds_read_b128 v[152:155], v195 offset:3072
	ds_read_b128 v[156:159], v196
	ds_read_b128 v[160:163], v196 offset:1024
	ds_read_b128 v[164:167], v196 offset:2048
	ds_read_b128 v[168:171], v196 offset:3072
	s_add_u32 s44, s44, s24
	s_addc_u32 s45, s45, s25
	s_mov_b32 m0, s46
	v_lshl_add_u64 v[228:229], s[44:45], 0, v[134:135]
	ds_read_b128 v[172:175], v194 offset:32768
	ds_read_b128 v[176:179], v194 offset:33792
	ds_read_b128 v[180:183], v194 offset:34816
	ds_read_b128 v[184:187], v194 offset:35840
	ds_read_b128 v[200:203], v194 offset:36864
	ds_read_b128 v[204:207], v194 offset:37888
	ds_read_b128 v[210:213], v194 offset:38912
	ds_read_b128 v[214:217], v194 offset:39936
	global_load_lds_dwordx4 v[228:229], off
	v_lshl_add_u64 v[228:229], s[44:45], 0, v[136:137]
	s_mov_b32 m0, s47
	s_nop 0
	global_load_lds_dwordx4 v[228:229], off
	s_waitcnt vmcnt(8)
	s_waitcnt lgkmcnt(0)
	s_barrier
	s_setprio 1
	s_waitcnt lgkmcnt(0)
	v_mfma_f32_16x16x32_bf16 v[126:129], v[140:143], v[172:175], v[126:129]
	v_mfma_f32_16x16x32_bf16 v[122:125], v[148:151], v[172:175], v[122:125]
	v_mfma_f32_16x16x32_bf16 v[110:113], v[140:143], v[180:183], v[110:113]
	v_mfma_f32_16x16x32_bf16 v[106:109], v[148:151], v[180:183], v[106:109]
	v_mfma_f32_16x16x32_bf16 v[94:97], v[140:143], v[200:203], v[94:97]
	v_mfma_f32_16x16x32_bf16 v[90:93], v[148:151], v[200:203], v[90:93]
	v_mfma_f32_16x16x32_bf16 v[78:81], v[140:143], v[210:213], v[78:81]
	v_mfma_f32_16x16x32_bf16 v[74:77], v[148:151], v[210:213], v[74:77]
	v_mfma_f32_16x16x32_bf16 v[126:129], v[144:147], v[176:179], v[126:129]
	v_mfma_f32_16x16x32_bf16 v[122:125], v[152:155], v[176:179], v[122:125]
	v_mfma_f32_16x16x32_bf16 v[110:113], v[144:147], v[184:187], v[110:113]
	v_mfma_f32_16x16x32_bf16 v[106:109], v[152:155], v[184:187], v[106:109]
	v_mfma_f32_16x16x32_bf16 v[94:97], v[144:147], v[204:207], v[94:97]
	v_mfma_f32_16x16x32_bf16 v[90:93], v[152:155], v[204:207], v[90:93]
	v_mfma_f32_16x16x32_bf16 v[78:81], v[144:147], v[214:217], v[78:81]
	v_mfma_f32_16x16x32_bf16 v[74:77], v[152:155], v[214:217], v[74:77]
	s_setprio 0
	s_setprio 1
	v_mfma_f32_16x16x32_bf16 v[118:121], v[156:159], v[172:175], v[118:121]
	v_mfma_f32_16x16x32_bf16 v[114:117], v[164:167], v[172:175], v[114:117]
	v_mfma_f32_16x16x32_bf16 v[102:105], v[156:159], v[180:183], v[102:105]
	v_mfma_f32_16x16x32_bf16 v[98:101], v[164:167], v[180:183], v[98:101]
	v_mfma_f32_16x16x32_bf16 v[86:89], v[156:159], v[200:203], v[86:89]
	v_mfma_f32_16x16x32_bf16 v[82:85], v[164:167], v[200:203], v[82:85]
	v_mfma_f32_16x16x32_bf16 v[70:73], v[156:159], v[210:213], v[70:73]
	v_mfma_f32_16x16x32_bf16 v[66:69], v[164:167], v[210:213], v[66:69]
	v_mfma_f32_16x16x32_bf16 v[118:121], v[160:163], v[176:179], v[118:121]
	v_mfma_f32_16x16x32_bf16 v[114:117], v[168:171], v[176:179], v[114:117]
	v_mfma_f32_16x16x32_bf16 v[102:105], v[160:163], v[184:187], v[102:105]
	v_mfma_f32_16x16x32_bf16 v[98:101], v[168:171], v[184:187], v[98:101]
	v_mfma_f32_16x16x32_bf16 v[86:89], v[160:163], v[204:207], v[86:89]
	v_mfma_f32_16x16x32_bf16 v[82:85], v[168:171], v[204:207], v[82:85]
	v_mfma_f32_16x16x32_bf16 v[70:73], v[160:163], v[214:217], v[70:73]
	v_mfma_f32_16x16x32_bf16 v[66:69], v[168:171], v[214:217], v[66:69]
	s_setprio 2
	s_barrier
	s_mov_b32 m0, s62
	v_lshl_add_u64 v[188:189], v[188:189], 0, s[18:19]
	ds_read_b128 v[172:175], v194 offset:49152
	ds_read_b128 v[176:179], v194 offset:50176
	ds_read_b128 v[180:183], v194 offset:51200
	ds_read_b128 v[184:187], v194 offset:52224
	ds_read_b128 v[200:203], v194 offset:53248
	ds_read_b128 v[204:207], v194 offset:54272
	ds_read_b128 v[210:213], v194 offset:55296
	ds_read_b128 v[214:217], v194 offset:56320
	global_load_lds_dwordx4 v[188:189], off
	v_lshl_add_u64 v[188:189], v[218:219], 0, s[18:19]
	s_mov_b32 m0, s63
	s_nop 0
	global_load_lds_dwordx4 v[188:189], off
	v_lshl_add_u64 v[188:189], v[220:221], 0, s[18:19]
	s_mov_b32 m0, s64
	s_nop 0
	global_load_lds_dwordx4 v[188:189], off
	v_lshl_add_u64 v[188:189], v[222:223], 0, s[18:19]
	s_mov_b32 m0, s65
	s_nop 0
	global_load_lds_dwordx4 v[188:189], off
	v_lshl_add_u64 v[188:189], v[224:225], 0, s[18:19]
	s_mov_b32 m0, s50
	s_nop 0
	global_load_lds_dwordx4 v[188:189], off
	v_lshl_add_u64 v[188:189], v[226:227], 0, s[18:19]
	s_mov_b32 m0, s51
	s_nop 0
	global_load_lds_dwordx4 v[188:189], off
	s_waitcnt vmcnt(8)
	s_waitcnt lgkmcnt(0)
	s_barrier
	s_setprio 1
	s_waitcnt lgkmcnt(0)
	v_mfma_f32_16x16x32_bf16 v[62:65], v[140:143], v[172:175], v[62:65]
	v_mfma_f32_16x16x32_bf16 v[58:61], v[148:151], v[172:175], v[58:61]
	v_mfma_f32_16x16x32_bf16 v[46:49], v[140:143], v[180:183], v[46:49]
	v_mfma_f32_16x16x32_bf16 v[42:45], v[148:151], v[180:183], v[42:45]
	v_mfma_f32_16x16x32_bf16 v[30:33], v[140:143], v[200:203], v[30:33]
	v_mfma_f32_16x16x32_bf16 v[26:29], v[148:151], v[200:203], v[26:29]
	v_mfma_f32_16x16x32_bf16 v[14:17], v[140:143], v[210:213], v[14:17]
	v_mfma_f32_16x16x32_bf16 v[10:13], v[148:151], v[210:213], v[10:13]
	v_mfma_f32_16x16x32_bf16 v[62:65], v[144:147], v[176:179], v[62:65]
	v_mfma_f32_16x16x32_bf16 v[58:61], v[152:155], v[176:179], v[58:61]
	v_mfma_f32_16x16x32_bf16 v[46:49], v[144:147], v[184:187], v[46:49]
	v_mfma_f32_16x16x32_bf16 v[42:45], v[152:155], v[184:187], v[42:45]
	v_mfma_f32_16x16x32_bf16 v[30:33], v[144:147], v[204:207], v[30:33]
	v_mfma_f32_16x16x32_bf16 v[26:29], v[152:155], v[204:207], v[26:29]
	v_mfma_f32_16x16x32_bf16 v[14:17], v[144:147], v[214:217], v[14:17]
	v_mfma_f32_16x16x32_bf16 v[10:13], v[152:155], v[214:217], v[10:13]
	s_setprio 0
	s_setprio 1
	v_mfma_f32_16x16x32_bf16 v[54:57], v[156:159], v[172:175], v[54:57]
	v_mfma_f32_16x16x32_bf16 v[50:53], v[164:167], v[172:175], v[50:53]
	v_mfma_f32_16x16x32_bf16 v[38:41], v[156:159], v[180:183], v[38:41]
	v_mfma_f32_16x16x32_bf16 v[34:37], v[164:167], v[180:183], v[34:37]
	v_mfma_f32_16x16x32_bf16 v[22:25], v[156:159], v[200:203], v[22:25]
	v_mfma_f32_16x16x32_bf16 v[18:21], v[164:167], v[200:203], v[18:21]
	v_mfma_f32_16x16x32_bf16 v[6:9], v[156:159], v[210:213], v[6:9]
	v_mfma_f32_16x16x32_bf16 v[2:5], v[164:167], v[210:213], v[2:5]
	v_mfma_f32_16x16x32_bf16 v[54:57], v[160:163], v[176:179], v[54:57]
	v_mfma_f32_16x16x32_bf16 v[50:53], v[168:171], v[176:179], v[50:53]
	v_mfma_f32_16x16x32_bf16 v[38:41], v[160:163], v[184:187], v[38:41]
	v_mfma_f32_16x16x32_bf16 v[34:37], v[168:171], v[184:187], v[34:37]
	v_mfma_f32_16x16x32_bf16 v[22:25], v[160:163], v[204:207], v[22:25]
	v_mfma_f32_16x16x32_bf16 v[18:21], v[168:171], v[204:207], v[18:21]
	v_mfma_f32_16x16x32_bf16 v[6:9], v[160:163], v[214:217], v[6:9]
	v_mfma_f32_16x16x32_bf16 v[2:5], v[168:171], v[214:217], v[2:5]
	s_setprio 2
	s_barrier
	s_cmp_ge_i32 s36, s54
	s_mov_b32 s44, s36
	s_cbranch_scc0 .LBB0_1446
	v_readlane_b32 s72, v235, 8
	v_readlane_b32 s74, v235, 10
	v_readlane_b32 s75, v235, 11
	v_readlane_b32 s86, v235, 22
	v_readlane_b32 s87, v235, 23
	s_mov_b64 s[74:75], s[86:87]
	v_readlane_b32 s73, v235, 9
	v_readlane_b32 s76, v235, 12
	v_readlane_b32 s77, v235, 13
	v_readlane_b32 s78, v235, 14
	v_readlane_b32 s79, v235, 15
	v_readlane_b32 s80, v235, 16
	v_readlane_b32 s81, v235, 17
	v_readlane_b32 s82, v235, 18
	v_readlane_b32 s83, v235, 19
	v_readlane_b32 s84, v235, 20
	v_readlane_b32 s85, v235, 21
